# plus GEMM loops: A-fragment LDS reads double-buffered with counted lgkmcnt (FFN-up, FFN-down/out-proj, even in-proj)
# speedup vs baseline: 1.0160x; 1.0160x over previous
.LBB0_297:
	s_barrier
	s_waitcnt vmcnt(11)
	ds_write_b128 v245, v[0:3]
	s_waitcnt vmcnt(10)
	ds_write_b128 v245, v[4:7] offset:5120
	s_waitcnt vmcnt(9)
	ds_write_b128 v245, v[8:11] offset:10240
	s_waitcnt vmcnt(8)
	ds_write_b128 v245, v[12:15] offset:15360
	s_waitcnt vmcnt(7)
	ds_write_b128 v245, v[16:19] offset:20480
	s_waitcnt vmcnt(6)
	ds_write_b128 v245, v[20:23] offset:25600
	s_waitcnt vmcnt(5)
	ds_write_b128 v245, v[24:27] offset:30720
	s_waitcnt vmcnt(4)
	ds_write_b128 v245, v[28:31] offset:35840
	s_waitcnt vmcnt(3)
	ds_write_b128 v245, v[32:35] offset:40960
	s_waitcnt vmcnt(2)
	ds_write_b128 v245, v[36:39] offset:46080
	s_waitcnt vmcnt(1)
	ds_write_b128 v245, v[40:43] offset:51200
	s_waitcnt vmcnt(0)
	ds_write_b128 v245, v[44:47] offset:56320
	v_lshl_add_u64 v[0:1], v[202:203], 0, s[6:7]
	v_lshl_add_u64 v[4:5], v[204:205], 0, s[6:7]
	v_lshl_add_u64 v[8:9], v[206:207], 0, s[6:7]
	v_lshl_add_u64 v[12:13], v[208:209], 0, s[6:7]
	v_lshl_add_u64 v[16:17], v[210:211], 0, s[6:7]
	v_lshl_add_u64 v[20:21], v[212:213], 0, s[6:7]
	v_lshl_add_u64 v[24:25], v[214:215], 0, s[6:7]
	v_lshl_add_u64 v[28:29], v[216:217], 0, s[6:7]
	v_lshl_add_u64 v[32:33], v[218:219], 0, s[6:7]
	v_lshl_add_u64 v[36:37], v[220:221], 0, s[6:7]
	v_lshl_add_u64 v[40:41], v[222:223], 0, s[6:7]
	v_lshl_add_u64 v[44:45], v[224:225], 0, s[6:7]
	s_waitcnt lgkmcnt(0)
	s_barrier
	global_load_dwordx4 v[0:3], v[0:1], off
	s_nop 0
	global_load_dwordx4 v[4:7], v[4:5], off
	s_nop 0
	global_load_dwordx4 v[8:11], v[8:9], off
	s_nop 0
	global_load_dwordx4 v[12:15], v[12:13], off
	s_nop 0
	global_load_dwordx4 v[16:19], v[16:17], off
	s_nop 0
	global_load_dwordx4 v[20:23], v[20:21], off
	s_nop 0
	global_load_dwordx4 v[24:27], v[24:25], off
	s_nop 0
	global_load_dwordx4 v[28:31], v[28:29], off
	s_nop 0
	global_load_dwordx4 v[32:35], v[32:33], off
	s_nop 0
	global_load_dwordx4 v[36:39], v[36:37], off
	s_nop 0
	global_load_dwordx4 v[40:43], v[40:41], off
	s_nop 0
	global_load_dwordx4 v[44:47], v[44:45], off
	ds_read_b128 v[176:179], v246 offset:40960
	ds_read_b128 v[184:187], v246 offset:43520
	ds_read_b128 v[188:191], v246 offset:46080
	ds_read_b128 v[230:233], v246 offset:48640
	ds_read_b128 v[180:183], v238
	ds_read_b128 v[248:251], v238 offset:2560
	s_add_u32 s6, s6, 0x80
	s_addc_u32 s7, s7, 0
	s_waitcnt lgkmcnt(1)
	v_mfma_f32_16x16x32_bf16 v[60:63], v[176:179], v[180:183], v[60:63]
	v_mfma_f32_16x16x32_bf16 v[64:67], v[184:187], v[180:183], v[64:67]
	v_mfma_f32_16x16x32_bf16 v[68:71], v[188:191], v[180:183], v[68:71]
	v_mfma_f32_16x16x32_bf16 v[76:79], v[230:233], v[180:183], v[76:79]
	ds_read_b128 v[180:183], v238 offset:5120
	s_waitcnt lgkmcnt(1)
	v_mfma_f32_16x16x32_bf16 v[72:75], v[176:179], v[248:251], v[72:75]
	v_mfma_f32_16x16x32_bf16 v[56:59], v[184:187], v[248:251], v[56:59]
	v_mfma_f32_16x16x32_bf16 v[52:55], v[188:191], v[248:251], v[52:55]
	v_mfma_f32_16x16x32_bf16 v[48:51], v[230:233], v[248:251], v[48:51]
	ds_read_b128 v[248:251], v238 offset:7680
	s_waitcnt lgkmcnt(1)
	v_mfma_f32_16x16x32_bf16 v[104:107], v[176:179], v[180:183], v[104:107]
	v_mfma_f32_16x16x32_bf16 v[92:95], v[184:187], v[180:183], v[92:95]
	v_mfma_f32_16x16x32_bf16 v[84:87], v[188:191], v[180:183], v[84:87]
	v_mfma_f32_16x16x32_bf16 v[80:83], v[230:233], v[180:183], v[80:83]
	ds_read_b128 v[180:183], v238 offset:10240
	s_waitcnt lgkmcnt(1)
	v_mfma_f32_16x16x32_bf16 v[120:123], v[176:179], v[248:251], v[120:123]
	v_mfma_f32_16x16x32_bf16 v[108:111], v[184:187], v[248:251], v[108:111]
	v_mfma_f32_16x16x32_bf16 v[96:99], v[188:191], v[248:251], v[96:99]
	v_mfma_f32_16x16x32_bf16 v[88:91], v[230:233], v[248:251], v[88:91]
	ds_read_b128 v[248:251], v238 offset:12800
	s_waitcnt lgkmcnt(1)
	v_mfma_f32_16x16x32_bf16 v[132:135], v[176:179], v[180:183], v[132:135]
	v_mfma_f32_16x16x32_bf16 v[124:127], v[184:187], v[180:183], v[124:127]
	v_mfma_f32_16x16x32_bf16 v[112:115], v[188:191], v[180:183], v[112:115]
	v_mfma_f32_16x16x32_bf16 v[100:103], v[230:233], v[180:183], v[100:103]
	ds_read_b128 v[180:183], v238 offset:15360
	s_waitcnt lgkmcnt(1)
	v_mfma_f32_16x16x32_bf16 v[140:143], v[176:179], v[248:251], v[140:143]
	v_mfma_f32_16x16x32_bf16 v[136:139], v[184:187], v[248:251], v[136:139]
	v_mfma_f32_16x16x32_bf16 v[128:131], v[188:191], v[248:251], v[128:131]
	v_mfma_f32_16x16x32_bf16 v[116:119], v[230:233], v[248:251], v[116:119]
	ds_read_b128 v[248:251], v247
	s_waitcnt lgkmcnt(1)
	v_mfma_f32_16x16x32_bf16 v[156:159], v[176:179], v[180:183], v[156:159]
	v_mfma_f32_16x16x32_bf16 v[152:155], v[184:187], v[180:183], v[152:155]
	v_mfma_f32_16x16x32_bf16 v[148:151], v[188:191], v[180:183], v[148:151]
	v_mfma_f32_16x16x32_bf16 v[144:147], v[230:233], v[180:183], v[144:147]
	ds_read_b128 v[180:183], v238 offset:64
	s_waitcnt lgkmcnt(1)
	v_mfma_f32_16x16x32_bf16 v[172:175], v[176:179], v[248:251], v[172:175]
	ds_read_b128 v[176:179], v246 offset:41024
	v_mfma_f32_16x16x32_bf16 v[168:171], v[184:187], v[248:251], v[168:171]
	ds_read_b128 v[184:187], v246 offset:43584
	v_mfma_f32_16x16x32_bf16 v[164:167], v[188:191], v[248:251], v[164:167]
	ds_read_b128 v[188:191], v246 offset:46144
	v_mfma_f32_16x16x32_bf16 v[160:163], v[230:233], v[248:251], v[160:163]
	ds_read_b128 v[230:233], v246 offset:48704
	ds_read_b128 v[248:251], v238 offset:2624
	s_waitcnt lgkmcnt(1)
	v_mfma_f32_16x16x32_bf16 v[60:63], v[176:179], v[180:183], v[60:63]
	v_mfma_f32_16x16x32_bf16 v[64:67], v[184:187], v[180:183], v[64:67]
	v_mfma_f32_16x16x32_bf16 v[68:71], v[188:191], v[180:183], v[68:71]
	v_mfma_f32_16x16x32_bf16 v[76:79], v[230:233], v[180:183], v[76:79]
	ds_read_b128 v[180:183], v238 offset:5184
	s_waitcnt lgkmcnt(1)
	v_mfma_f32_16x16x32_bf16 v[72:75], v[176:179], v[248:251], v[72:75]
	v_mfma_f32_16x16x32_bf16 v[56:59], v[184:187], v[248:251], v[56:59]
	v_mfma_f32_16x16x32_bf16 v[52:55], v[188:191], v[248:251], v[52:55]
	v_mfma_f32_16x16x32_bf16 v[48:51], v[230:233], v[248:251], v[48:51]
	ds_read_b128 v[248:251], v238 offset:7744
	s_waitcnt lgkmcnt(1)
	v_mfma_f32_16x16x32_bf16 v[104:107], v[176:179], v[180:183], v[104:107]
	v_mfma_f32_16x16x32_bf16 v[92:95], v[184:187], v[180:183], v[92:95]
	v_mfma_f32_16x16x32_bf16 v[84:87], v[188:191], v[180:183], v[84:87]
	v_mfma_f32_16x16x32_bf16 v[80:83], v[230:233], v[180:183], v[80:83]
	ds_read_b128 v[180:183], v238 offset:10304
	s_waitcnt lgkmcnt(1)
	v_mfma_f32_16x16x32_bf16 v[120:123], v[176:179], v[248:251], v[120:123]
	v_mfma_f32_16x16x32_bf16 v[108:111], v[184:187], v[248:251], v[108:111]
	v_mfma_f32_16x16x32_bf16 v[96:99], v[188:191], v[248:251], v[96:99]
	v_mfma_f32_16x16x32_bf16 v[88:91], v[230:233], v[248:251], v[88:91]
	ds_read_b128 v[248:251], v238 offset:12864
	s_waitcnt lgkmcnt(1)
	v_mfma_f32_16x16x32_bf16 v[132:135], v[176:179], v[180:183], v[132:135]
	v_mfma_f32_16x16x32_bf16 v[124:127], v[184:187], v[180:183], v[124:127]
	v_mfma_f32_16x16x32_bf16 v[112:115], v[188:191], v[180:183], v[112:115]
	v_mfma_f32_16x16x32_bf16 v[100:103], v[230:233], v[180:183], v[100:103]
	ds_read_b128 v[180:183], v238 offset:15424
	s_waitcnt lgkmcnt(1)
	v_mfma_f32_16x16x32_bf16 v[140:143], v[176:179], v[248:251], v[140:143]
	v_mfma_f32_16x16x32_bf16 v[136:139], v[184:187], v[248:251], v[136:139]
	v_mfma_f32_16x16x32_bf16 v[128:131], v[188:191], v[248:251], v[128:131]
	v_mfma_f32_16x16x32_bf16 v[116:119], v[230:233], v[248:251], v[116:119]
	ds_read_b128 v[248:251], v247 offset:64
	s_waitcnt lgkmcnt(1)
	v_mfma_f32_16x16x32_bf16 v[156:159], v[176:179], v[180:183], v[156:159]
	v_mfma_f32_16x16x32_bf16 v[152:155], v[184:187], v[180:183], v[152:155]
	v_mfma_f32_16x16x32_bf16 v[148:151], v[188:191], v[180:183], v[148:151]
	v_mfma_f32_16x16x32_bf16 v[144:147], v[230:233], v[180:183], v[144:147]
	s_waitcnt lgkmcnt(0)
	v_mfma_f32_16x16x32_bf16 v[172:175], v[176:179], v[248:251], v[172:175]
	v_mfma_f32_16x16x32_bf16 v[168:171], v[184:187], v[248:251], v[168:171]
	v_mfma_f32_16x16x32_bf16 v[164:167], v[188:191], v[248:251], v[164:167]
	v_mfma_f32_16x16x32_bf16 v[160:163], v[230:233], v[248:251], v[160:163]
	s_cmpk_eq_i32 s6, 0x780
	s_cbranch_scc0 .LBB0_297
	s_barrier
	s_waitcnt vmcnt(11)
	ds_write_b128 v245, v[0:3]
	s_waitcnt vmcnt(10)
	ds_write_b128 v245, v[4:7] offset:5120
	s_waitcnt vmcnt(9)
	ds_write_b128 v245, v[8:11] offset:10240
	s_waitcnt vmcnt(8)
	ds_write_b128 v245, v[12:15] offset:15360
	s_waitcnt vmcnt(7)
	ds_write_b128 v245, v[16:19] offset:20480
	s_waitcnt vmcnt(6)
	ds_write_b128 v245, v[20:23] offset:25600
	s_waitcnt vmcnt(5)
	ds_write_b128 v245, v[24:27] offset:30720
	s_waitcnt vmcnt(4)
	ds_write_b128 v245, v[28:31] offset:35840
	s_waitcnt vmcnt(3)
	ds_write_b128 v245, v[32:35] offset:40960
	s_waitcnt vmcnt(2)
	ds_write_b128 v245, v[36:39] offset:46080
	s_waitcnt vmcnt(1)
	ds_write_b128 v245, v[40:43] offset:51200
	s_waitcnt vmcnt(0)
	ds_write_b128 v245, v[44:47] offset:56320
	s_waitcnt lgkmcnt(0)
	s_barrier
	ds_read_b128 v[176:179], v246 offset:40960
	ds_read_b128 v[180:183], v246 offset:43520
	ds_read_b128 v[184:187], v246 offset:46080
	ds_read_b128 v[188:191], v246 offset:48640
	ds_read_b128 v[0:3], v238 offset:2560
	ds_read_b128 v[4:7], v238 offset:5120
	ds_read_b128 v[8:11], v238
	s_add_i32 s2, s10, 0xfffffe00
	s_cmpk_lt_u32 s2, 0x400
	s_waitcnt lgkmcnt(2)
	v_mfma_f32_16x16x32_bf16 v[218:221], v[176:179], v[0:3], v[72:75]
	v_or_b32_e32 v196, s10, v240
	ds_read_b128 v[20:23], v238 offset:15360
	s_waitcnt lgkmcnt(1)
	v_mfma_f32_16x16x32_bf16 v[202:205], v[176:179], v[8:11], v[60:63]
	v_mfma_f32_16x16x32_bf16 v[206:209], v[180:183], v[8:11], v[64:67]
	v_mfma_f32_16x16x32_bf16 v[210:213], v[184:187], v[8:11], v[68:71]
	v_mfma_f32_16x16x32_bf16 v[214:217], v[188:191], v[8:11], v[76:79]
	ds_read_b128 v[8:11], v238 offset:7680
	v_mfma_f32_16x16x32_bf16 v[222:225], v[180:183], v[0:3], v[56:59]
	v_mfma_f32_16x16x32_bf16 v[248:251], v[184:187], v[0:3], v[52:55]
	v_mfma_f32_16x16x32_bf16 v[230:233], v[188:191], v[0:3], v[48:51]
	ds_read_b128 v[0:3], v238 offset:10240
	v_mfma_f32_16x16x32_bf16 v[64:67], v[176:179], v[4:7], v[104:107]
	v_mfma_f32_16x16x32_bf16 v[68:71], v[180:183], v[4:7], v[92:95]
	v_mfma_f32_16x16x32_bf16 v[72:75], v[184:187], v[4:7], v[84:87]
	v_mfma_f32_16x16x32_bf16 v[76:79], v[188:191], v[4:7], v[80:83]
	ds_read_b128 v[4:7], v238 offset:12800
	s_nop 1
	ds_read_b128 v[80:83], v247
	s_waitcnt lgkmcnt(3)
	v_mfma_f32_16x16x32_bf16 v[48:51], v[176:179], v[8:11], v[120:123]
	v_mfma_f32_16x16x32_bf16 v[52:55], v[180:183], v[8:11], v[108:111]
	v_mfma_f32_16x16x32_bf16 v[56:59], v[184:187], v[8:11], v[96:99]
	v_mfma_f32_16x16x32_bf16 v[60:63], v[188:191], v[8:11], v[88:91]
	s_waitcnt lgkmcnt(2)
	v_mfma_f32_16x16x32_bf16 v[32:35], v[176:179], v[0:3], v[132:135]
	v_mfma_f32_16x16x32_bf16 v[36:39], v[180:183], v[0:3], v[124:127]
	v_mfma_f32_16x16x32_bf16 v[40:43], v[184:187], v[0:3], v[112:115]
	v_mfma_f32_16x16x32_bf16 v[44:47], v[188:191], v[0:3], v[100:103]
	s_waitcnt lgkmcnt(1)
	v_mfma_f32_16x16x32_bf16 v[0:3], v[184:187], v[4:7], v[128:131]
	v_mfma_f32_16x16x32_bf16 v[8:11], v[176:179], v[20:23], v[156:159]
	v_mfma_f32_16x16x32_bf16 v[12:15], v[180:183], v[20:23], v[152:155]
	v_mfma_f32_16x16x32_bf16 v[16:19], v[184:187], v[20:23], v[148:151]
	v_mfma_f32_16x16x32_bf16 v[20:23], v[188:191], v[20:23], v[144:147]
	s_waitcnt lgkmcnt(0)
	v_mfma_f32_16x16x32_bf16 v[120:123], v[176:179], v[80:83], v[172:175]
	v_mfma_f32_16x16x32_bf16 v[124:127], v[180:183], v[80:83], v[168:171]
	v_mfma_f32_16x16x32_bf16 v[128:131], v[184:187], v[80:83], v[164:167]
	v_mfma_f32_16x16x32_bf16 v[132:135], v[188:191], v[80:83], v[160:163]
	ds_read_b128 v[144:147], v246 offset:41024
	ds_read_b128 v[148:151], v246 offset:43584
	ds_read_b128 v[152:155], v246 offset:46144
	ds_read_b128 v[156:159], v246 offset:48704
	ds_read_b128 v[80:83], v238 offset:2624
	ds_read_b128 v[84:87], v238 offset:5184
	ds_read_b128 v[88:91], v238 offset:64
	ds_read_b128 v[160:163], v238 offset:7744
	ds_read_b128 v[164:167], v238 offset:10304
	v_mfma_f32_16x16x32_bf16 v[24:27], v[176:179], v[4:7], v[140:143]
	ds_read_b128 v[168:171], v238 offset:12864
	v_mfma_f32_16x16x32_bf16 v[28:31], v[180:183], v[4:7], v[136:139]
	v_mfma_f32_16x16x32_bf16 v[4:7], v[188:191], v[4:7], v[116:119]
	s_waitcnt lgkmcnt(3)
	v_mfma_f32_16x16x32_bf16 v[140:143], v[144:147], v[88:91], v[202:205]
	v_mfma_f32_16x16x32_bf16 v[136:139], v[148:151], v[88:91], v[206:209]
	v_mfma_f32_16x16x32_bf16 v[116:119], v[152:155], v[88:91], v[210:213]
	v_mfma_f32_16x16x32_bf16 v[104:107], v[156:159], v[88:91], v[214:217]
	v_mfma_f32_16x16x32_bf16 v[108:111], v[144:147], v[80:83], v[218:221]
	v_mfma_f32_16x16x32_bf16 v[112:115], v[148:151], v[80:83], v[222:225]
	v_mfma_f32_16x16x32_bf16 v[96:99], v[152:155], v[80:83], v[248:251]
	v_mfma_f32_16x16x32_bf16 v[100:103], v[156:159], v[80:83], v[230:233]
	v_mfma_f32_16x16x32_bf16 v[88:91], v[144:147], v[84:87], v[64:67]
	v_mfma_f32_16x16x32_bf16 v[92:95], v[148:151], v[84:87], v[68:71]
	v_mfma_f32_16x16x32_bf16 v[80:83], v[152:155], v[84:87], v[72:75]
	v_mfma_f32_16x16x32_bf16 v[84:87], v[156:159], v[84:87], v[76:79]
	s_waitcnt lgkmcnt(2)
	v_mfma_f32_16x16x32_bf16 v[72:75], v[144:147], v[160:163], v[48:51]
	v_mfma_f32_16x16x32_bf16 v[76:79], v[148:151], v[160:163], v[52:55]
	v_mfma_f32_16x16x32_bf16 v[64:67], v[152:155], v[160:163], v[56:59]
	v_mfma_f32_16x16x32_bf16 v[68:71], v[156:159], v[160:163], v[60:63]
	ds_read_b128 v[160:163], v238 offset:15424
	s_waitcnt lgkmcnt(2)
	v_mfma_f32_16x16x32_bf16 v[56:59], v[144:147], v[164:167], v[32:35]
	v_mfma_f32_16x16x32_bf16 v[60:63], v[148:151], v[164:167], v[36:39]
	v_mfma_f32_16x16x32_bf16 v[40:43], v[152:155], v[164:167], v[40:43]
	v_mfma_f32_16x16x32_bf16 v[44:47], v[156:159], v[164:167], v[44:47]
	ds_read_b128 v[164:167], v247 offset:64
	s_waitcnt lgkmcnt(2)
	v_mfma_f32_16x16x32_bf16 v[48:51], v[144:147], v[168:171], v[24:27]
	s_waitcnt lgkmcnt(1)
	v_mfma_f32_16x16x32_bf16 v[24:27], v[144:147], v[160:163], v[8:11]
	s_waitcnt lgkmcnt(0)
	v_mfma_f32_16x16x32_bf16 v[8:11], v[144:147], v[164:167], v[120:123]
	s_nop 2
	v_add_u32_e32 v120, s8, v239
	v_mfma_f32_16x16x32_bf16 v[52:55], v[148:151], v[168:171], v[28:31]
	s_cselect_b64 s[8:9], -1, 0
	s_cmpk_lt_u32 s10, 0x400
	s_cselect_b64 s[6:7], -1, 0
	v_mfma_f32_16x16x32_bf16 v[28:31], v[148:151], v[160:163], v[12:15]
	v_mfma_f32_16x16x32_bf16 v[12:15], v[148:151], v[164:167], v[124:127]
	s_nop 2
	v_or_b32_e32 v125, v120, v226
	v_lshlrev_b32_e32 v120, 1, v120
	v_and_b32_e32 v120, 0xfffffe00, v120
	v_add_u32_e32 v124, s14, v120
	v_mov_b64_e32 v[120:121], s[44:45]
	v_mad_i64_i32 v[120:121], s[2:3], v125, s70, v[120:121]
	s_movk_i32 s2, 0x2000
	s_nop 0
	v_cmp_gt_i32_e32 vcc, s2, v125
	s_movk_i32 s2, 0x8f
	v_and_or_b32 v122, v125, s2, v124
	v_mfma_f32_16x16x32_bf16 v[32:35], v[152:155], v[168:171], v[0:3]
	v_ashrrev_i32_e32 v123, 31, v122
	v_lshlrev_b64 v[126:127], 11, v[122:123]
	v_lshlrev_b32_e32 v122, 1, v196
	v_mfma_f32_16x16x32_bf16 v[36:39], v[156:159], v[168:171], v[4:7]
	v_mov_b32_e32 v123, v197
	v_lshl_add_u64 v[122:123], v[120:121], 0, v[122:123]
	v_lshl_add_u64 v[120:121], s[88:89], 0, v[126:127]
	v_mfma_f32_16x16x32_bf16 v[16:19], v[152:155], v[160:163], v[16:19]
	s_and_b64 s[10:11], vcc, s[8:9]
	v_lshl_add_u64 v[120:121], v[196:197], 2, v[120:121]
	v_mfma_f32_16x16x32_bf16 v[20:23], v[156:159], v[160:163], v[20:23]
	v_mfma_f32_16x16x32_bf16 v[0:3], v[152:155], v[164:167], v[128:131]
	v_mfma_f32_16x16x32_bf16 v[4:7], v[156:159], v[164:167], v[132:135]
	s_nop 1
	v_cvt_pk_bf16_f32 v128, v140, v141
	v_cvt_pk_bf16_f32 v129, v142, v143
	global_store_dwordx2 v[122:123], v[128:129], off
	s_and_saveexec_b64 s[12:13], s[10:11]
	s_cbranch_execz .LBB0_300
	s_and_b64 s[2:3], s[6:7], exec
	s_mov_b32 s2, 0x3fff800
	s_cselect_b32 s50, s2, 0x5fff000
	v_lshl_add_u64 v[126:127], v[120:121], 0, s[50:51]
	global_store_dwordx4 v[126:127], v[140:143], off

.LBB0_851:
	s_waitcnt vmcnt(63) expcnt(7) lgkmcnt(15)
	s_barrier
	s_waitcnt vmcnt(11)
	ds_write_b128 v245, v[0:3]
	s_waitcnt vmcnt(10)
	ds_write_b128 v245, v[4:7] offset:5120
	s_waitcnt vmcnt(9)
	ds_write_b128 v245, v[8:11] offset:10240
	s_waitcnt vmcnt(8)
	ds_write_b128 v245, v[12:15] offset:15360
	s_waitcnt vmcnt(7)
	ds_write_b128 v245, v[16:19] offset:20480
	s_waitcnt vmcnt(6)
	ds_write_b128 v245, v[20:23] offset:25600
	s_waitcnt vmcnt(5)
	ds_write_b128 v245, v[24:27] offset:30720
	s_waitcnt vmcnt(4)
	ds_write_b128 v245, v[28:31] offset:35840
	s_waitcnt vmcnt(3)
	ds_write_b128 v245, v[32:35] offset:40960
	s_waitcnt vmcnt(2)
	ds_write_b128 v245, v[36:39] offset:46080
	s_waitcnt vmcnt(1)
	ds_write_b128 v245, v[40:43] offset:51200
	s_waitcnt vmcnt(0)
	ds_write_b128 v245, v[44:47] offset:56320
	v_lshl_add_u64 v[0:1], v[192:193], 0, s[8:9]
	v_lshl_add_u64 v[4:5], v[194:195], 0, s[8:9]
	v_lshl_add_u64 v[8:9], v[208:209], 0, s[8:9]
	v_lshl_add_u64 v[12:13], v[210:211], 0, s[8:9]
	v_lshl_add_u64 v[16:17], v[212:213], 0, s[8:9]
	v_lshl_add_u64 v[20:21], v[214:215], 0, s[8:9]
	v_lshl_add_u64 v[24:25], v[216:217], 0, s[8:9]
	v_lshl_add_u64 v[28:29], v[218:219], 0, s[8:9]
	v_lshl_add_u64 v[32:33], v[220:221], 0, s[8:9]
	v_lshl_add_u64 v[36:37], v[222:223], 0, s[8:9]
	v_lshl_add_u64 v[40:41], v[224:225], 0, s[8:9]
	v_lshl_add_u64 v[44:45], v[226:227], 0, s[8:9]
	s_waitcnt lgkmcnt(0)
	s_barrier
	global_load_dwordx4 v[0:3], v[0:1], off
	s_nop 0
	global_load_dwordx4 v[4:7], v[4:5], off
	s_nop 0
	global_load_dwordx4 v[8:11], v[8:9], off
	s_nop 0
	global_load_dwordx4 v[12:15], v[12:13], off
	s_nop 0
	global_load_dwordx4 v[16:19], v[16:17], off
	s_nop 0
	global_load_dwordx4 v[20:23], v[20:21], off
	s_nop 0
	global_load_dwordx4 v[24:27], v[24:25], off
	s_nop 0
	global_load_dwordx4 v[28:31], v[28:29], off
	s_nop 0
	global_load_dwordx4 v[32:35], v[32:33], off
	s_nop 0
	global_load_dwordx4 v[36:39], v[36:37], off
	s_nop 0
	global_load_dwordx4 v[40:43], v[40:41], off
	s_nop 0
	global_load_dwordx4 v[44:47], v[44:45], off
	ds_read_b128 v[176:179], v246 offset:40960
	ds_read_b128 v[184:187], v246 offset:43520
	ds_read_b128 v[188:191], v246 offset:46080
	ds_read_b128 v[230:233], v246 offset:48640
	ds_read_b128 v[180:183], v241
	ds_read_b128 v[248:251], v241 offset:2560
	s_add_u32 s8, s8, 0x80
	s_addc_u32 s9, s9, 0
	s_waitcnt lgkmcnt(1)
	v_mfma_f32_16x16x32_bf16 v[48:51], v[176:179], v[180:183], v[48:51]
	v_mfma_f32_16x16x32_bf16 v[72:75], v[184:187], v[180:183], v[72:75]
	v_mfma_f32_16x16x32_bf16 v[80:83], v[188:191], v[180:183], v[80:83]
	v_mfma_f32_16x16x32_bf16 v[88:91], v[230:233], v[180:183], v[88:91]
	ds_read_b128 v[180:183], v241 offset:5120
	s_waitcnt lgkmcnt(1)
	v_mfma_f32_16x16x32_bf16 v[84:87], v[176:179], v[248:251], v[84:87]
	v_mfma_f32_16x16x32_bf16 v[64:67], v[184:187], v[248:251], v[64:67]
	v_mfma_f32_16x16x32_bf16 v[56:59], v[188:191], v[248:251], v[56:59]
	v_mfma_f32_16x16x32_bf16 v[52:55], v[230:233], v[248:251], v[52:55]
	ds_read_b128 v[248:251], v241 offset:7680
	s_waitcnt lgkmcnt(1)
	v_mfma_f32_16x16x32_bf16 v[104:107], v[176:179], v[180:183], v[104:107]
	v_mfma_f32_16x16x32_bf16 v[92:95], v[184:187], v[180:183], v[92:95]
	v_mfma_f32_16x16x32_bf16 v[68:71], v[188:191], v[180:183], v[68:71]
	v_mfma_f32_16x16x32_bf16 v[60:63], v[230:233], v[180:183], v[60:63]
	ds_read_b128 v[180:183], v241 offset:10240
	s_waitcnt lgkmcnt(1)
	v_mfma_f32_16x16x32_bf16 v[120:123], v[176:179], v[248:251], v[120:123]
	v_mfma_f32_16x16x32_bf16 v[108:111], v[184:187], v[248:251], v[108:111]
	v_mfma_f32_16x16x32_bf16 v[96:99], v[188:191], v[248:251], v[96:99]
	v_mfma_f32_16x16x32_bf16 v[76:79], v[230:233], v[248:251], v[76:79]
	ds_read_b128 v[248:251], v241 offset:12800
	s_waitcnt lgkmcnt(1)
	v_mfma_f32_16x16x32_bf16 v[132:135], v[176:179], v[180:183], v[132:135]
	v_mfma_f32_16x16x32_bf16 v[124:127], v[184:187], v[180:183], v[124:127]
	v_mfma_f32_16x16x32_bf16 v[112:115], v[188:191], v[180:183], v[112:115]
	v_mfma_f32_16x16x32_bf16 v[100:103], v[230:233], v[180:183], v[100:103]
	ds_read_b128 v[180:183], v241 offset:15360
	s_waitcnt lgkmcnt(1)
	v_mfma_f32_16x16x32_bf16 v[140:143], v[176:179], v[248:251], v[140:143]
	v_mfma_f32_16x16x32_bf16 v[136:139], v[184:187], v[248:251], v[136:139]
	v_mfma_f32_16x16x32_bf16 v[128:131], v[188:191], v[248:251], v[128:131]
	v_mfma_f32_16x16x32_bf16 v[116:119], v[230:233], v[248:251], v[116:119]
	ds_read_b128 v[248:251], v247
	s_waitcnt lgkmcnt(1)
	v_mfma_f32_16x16x32_bf16 v[156:159], v[176:179], v[180:183], v[156:159]
	v_mfma_f32_16x16x32_bf16 v[152:155], v[184:187], v[180:183], v[152:155]
	v_mfma_f32_16x16x32_bf16 v[148:151], v[188:191], v[180:183], v[148:151]
	v_mfma_f32_16x16x32_bf16 v[144:147], v[230:233], v[180:183], v[144:147]
	ds_read_b128 v[180:183], v241 offset:64
	s_waitcnt lgkmcnt(1)
	v_mfma_f32_16x16x32_bf16 v[172:175], v[176:179], v[248:251], v[172:175]
	ds_read_b128 v[176:179], v246 offset:41024
	v_mfma_f32_16x16x32_bf16 v[168:171], v[184:187], v[248:251], v[168:171]
	ds_read_b128 v[184:187], v246 offset:43584
	v_mfma_f32_16x16x32_bf16 v[164:167], v[188:191], v[248:251], v[164:167]
	ds_read_b128 v[188:191], v246 offset:46144
	v_mfma_f32_16x16x32_bf16 v[160:163], v[230:233], v[248:251], v[160:163]
	ds_read_b128 v[230:233], v246 offset:48704
	ds_read_b128 v[248:251], v241 offset:2624
	s_waitcnt lgkmcnt(1)
	v_mfma_f32_16x16x32_bf16 v[48:51], v[176:179], v[180:183], v[48:51]
	v_mfma_f32_16x16x32_bf16 v[72:75], v[184:187], v[180:183], v[72:75]
	v_mfma_f32_16x16x32_bf16 v[80:83], v[188:191], v[180:183], v[80:83]
	v_mfma_f32_16x16x32_bf16 v[88:91], v[230:233], v[180:183], v[88:91]
	ds_read_b128 v[180:183], v241 offset:5184
	s_waitcnt lgkmcnt(1)
	v_mfma_f32_16x16x32_bf16 v[84:87], v[176:179], v[248:251], v[84:87]
	v_mfma_f32_16x16x32_bf16 v[64:67], v[184:187], v[248:251], v[64:67]
	v_mfma_f32_16x16x32_bf16 v[56:59], v[188:191], v[248:251], v[56:59]
	v_mfma_f32_16x16x32_bf16 v[52:55], v[230:233], v[248:251], v[52:55]
	ds_read_b128 v[248:251], v241 offset:7744
	s_waitcnt lgkmcnt(1)
	v_mfma_f32_16x16x32_bf16 v[104:107], v[176:179], v[180:183], v[104:107]
	v_mfma_f32_16x16x32_bf16 v[92:95], v[184:187], v[180:183], v[92:95]
	v_mfma_f32_16x16x32_bf16 v[68:71], v[188:191], v[180:183], v[68:71]
	v_mfma_f32_16x16x32_bf16 v[60:63], v[230:233], v[180:183], v[60:63]
	ds_read_b128 v[180:183], v241 offset:10304
	s_waitcnt lgkmcnt(1)
	v_mfma_f32_16x16x32_bf16 v[120:123], v[176:179], v[248:251], v[120:123]
	v_mfma_f32_16x16x32_bf16 v[108:111], v[184:187], v[248:251], v[108:111]
	v_mfma_f32_16x16x32_bf16 v[96:99], v[188:191], v[248:251], v[96:99]
	v_mfma_f32_16x16x32_bf16 v[76:79], v[230:233], v[248:251], v[76:79]
	ds_read_b128 v[248:251], v241 offset:12864
	s_waitcnt lgkmcnt(1)
	v_mfma_f32_16x16x32_bf16 v[132:135], v[176:179], v[180:183], v[132:135]
	v_mfma_f32_16x16x32_bf16 v[124:127], v[184:187], v[180:183], v[124:127]
	v_mfma_f32_16x16x32_bf16 v[112:115], v[188:191], v[180:183], v[112:115]
	v_mfma_f32_16x16x32_bf16 v[100:103], v[230:233], v[180:183], v[100:103]
	ds_read_b128 v[180:183], v241 offset:15424
	s_waitcnt lgkmcnt(1)
	v_mfma_f32_16x16x32_bf16 v[140:143], v[176:179], v[248:251], v[140:143]
	v_mfma_f32_16x16x32_bf16 v[136:139], v[184:187], v[248:251], v[136:139]
	v_mfma_f32_16x16x32_bf16 v[128:131], v[188:191], v[248:251], v[128:131]
	v_mfma_f32_16x16x32_bf16 v[116:119], v[230:233], v[248:251], v[116:119]
	ds_read_b128 v[248:251], v247 offset:64
	s_waitcnt lgkmcnt(1)
	v_mfma_f32_16x16x32_bf16 v[156:159], v[176:179], v[180:183], v[156:159]
	v_mfma_f32_16x16x32_bf16 v[152:155], v[184:187], v[180:183], v[152:155]
	v_mfma_f32_16x16x32_bf16 v[148:151], v[188:191], v[180:183], v[148:151]
	v_mfma_f32_16x16x32_bf16 v[144:147], v[230:233], v[180:183], v[144:147]
	s_waitcnt lgkmcnt(0)
	v_mfma_f32_16x16x32_bf16 v[172:175], v[176:179], v[248:251], v[172:175]
	v_mfma_f32_16x16x32_bf16 v[168:171], v[184:187], v[248:251], v[168:171]
	v_mfma_f32_16x16x32_bf16 v[164:167], v[188:191], v[248:251], v[164:167]
	v_mfma_f32_16x16x32_bf16 v[160:163], v[230:233], v[248:251], v[160:163]
	s_cmpk_eq_i32 s8, 0x780
	s_cbranch_scc0 .LBB0_851
	s_barrier
	s_waitcnt vmcnt(11)
	ds_write_b128 v245, v[0:3]
	s_waitcnt vmcnt(10)
	ds_write_b128 v245, v[4:7] offset:5120
	s_waitcnt vmcnt(9)
	ds_write_b128 v245, v[8:11] offset:10240
	s_waitcnt vmcnt(8)
	ds_write_b128 v245, v[12:15] offset:15360
	s_waitcnt vmcnt(7)
	ds_write_b128 v245, v[16:19] offset:20480
	s_waitcnt vmcnt(6)
	ds_write_b128 v245, v[20:23] offset:25600
	s_waitcnt vmcnt(5)
	ds_write_b128 v245, v[24:27] offset:30720
	s_waitcnt vmcnt(4)
	ds_write_b128 v245, v[28:31] offset:35840
	s_waitcnt vmcnt(3)
	ds_write_b128 v245, v[32:35] offset:40960
	s_waitcnt vmcnt(2)
	ds_write_b128 v245, v[36:39] offset:46080
	s_waitcnt vmcnt(1)
	ds_write_b128 v245, v[40:43] offset:51200
	s_waitcnt vmcnt(0)
	ds_write_b128 v245, v[44:47] offset:56320
	s_waitcnt lgkmcnt(0)
	s_barrier
	ds_read_b128 v[208:211], v246 offset:40960
	ds_read_b128 v[212:215], v246 offset:43520
	ds_read_b128 v[216:219], v246 offset:46080
	ds_read_b128 v[220:223], v246 offset:48640
	ds_read_b128 v[0:3], v241
	ds_read_b128 v[4:7], v241 offset:2560
	ds_read_b128 v[8:11], v241 offset:5120
	ds_read_b128 v[12:15], v241 offset:12800
	v_or_b32_e32 v196, s14, v238
	s_waitcnt lgkmcnt(3)
	v_mfma_f32_16x16x32_bf16 v[180:183], v[208:211], v[0:3], v[48:51]
	s_add_i32 s12, s12, s53
	s_add_i32 s11, s11, s53
	v_mfma_f32_16x16x32_bf16 v[184:187], v[212:215], v[0:3], v[72:75]
	v_mfma_f32_16x16x32_bf16 v[188:191], v[216:219], v[0:3], v[80:83]
	v_mfma_f32_16x16x32_bf16 v[192:195], v[220:223], v[0:3], v[88:91]
	ds_read_b128 v[0:3], v241 offset:7680
	s_waitcnt lgkmcnt(3)
	v_mfma_f32_16x16x32_bf16 v[80:83], v[208:211], v[4:7], v[84:87]
	v_mfma_f32_16x16x32_bf16 v[84:87], v[212:215], v[4:7], v[64:67]
	v_mfma_f32_16x16x32_bf16 v[88:91], v[216:219], v[4:7], v[56:59]
	v_mfma_f32_16x16x32_bf16 v[176:179], v[220:223], v[4:7], v[52:55]
	ds_read_b128 v[4:7], v241 offset:10240
	s_waitcnt lgkmcnt(3)
	v_mfma_f32_16x16x32_bf16 v[72:75], v[212:215], v[8:11], v[92:95]
	s_waitcnt lgkmcnt(1)
	v_mfma_f32_16x16x32_bf16 v[56:59], v[220:223], v[0:3], v[76:79]
	s_nop 0
	ds_read_b128 v[92:95], v247
	s_nop 0
	ds_read_b128 v[76:79], v241 offset:15360
	v_mfma_f32_16x16x32_bf16 v[64:67], v[208:211], v[8:11], v[104:107]
	v_mfma_f32_16x16x32_bf16 v[68:71], v[216:219], v[8:11], v[68:71]
	v_mfma_f32_16x16x32_bf16 v[60:63], v[220:223], v[8:11], v[60:63]
	v_mfma_f32_16x16x32_bf16 v[44:47], v[208:211], v[0:3], v[120:123]
	s_waitcnt lgkmcnt(2)
	v_mfma_f32_16x16x32_bf16 v[28:31], v[208:211], v[4:7], v[132:135]
	v_mfma_f32_16x16x32_bf16 v[32:35], v[212:215], v[4:7], v[124:127]
	v_mfma_f32_16x16x32_bf16 v[36:39], v[216:219], v[4:7], v[112:115]
	v_mfma_f32_16x16x32_bf16 v[40:43], v[220:223], v[4:7], v[100:103]
	v_mfma_f32_16x16x32_bf16 v[4:7], v[212:215], v[12:15], v[136:139]
	v_mfma_f32_16x16x32_bf16 v[8:11], v[216:219], v[12:15], v[128:131]
	s_waitcnt lgkmcnt(0)
	v_mfma_f32_16x16x32_bf16 v[16:19], v[208:211], v[76:79], v[156:159]
	v_mfma_f32_16x16x32_bf16 v[20:23], v[212:215], v[76:79], v[152:155]
	v_mfma_f32_16x16x32_bf16 v[24:27], v[216:219], v[76:79], v[148:151]
	v_mfma_f32_16x16x32_bf16 v[120:123], v[220:223], v[76:79], v[144:147]
	v_mfma_f32_16x16x32_bf16 v[124:127], v[208:211], v[92:95], v[172:175]
	v_mfma_f32_16x16x32_bf16 v[128:131], v[212:215], v[92:95], v[168:171]
	v_mfma_f32_16x16x32_bf16 v[132:135], v[216:219], v[92:95], v[164:167]
	v_mfma_f32_16x16x32_bf16 v[136:139], v[220:223], v[92:95], v[160:163]
	ds_read_b128 v[148:151], v246 offset:41024
	ds_read_b128 v[152:155], v246 offset:43584
	ds_read_b128 v[156:159], v246 offset:46144
	ds_read_b128 v[160:163], v246 offset:48704
	ds_read_b128 v[76:79], v241 offset:64
	ds_read_b128 v[92:95], v241 offset:2624
	ds_read_b128 v[164:167], v241 offset:5184
	ds_read_b128 v[168:171], v241 offset:7744
	ds_read_b128 v[172:175], v241 offset:10304
	v_mfma_f32_16x16x32_bf16 v[48:51], v[212:215], v[0:3], v[108:111]
	v_mfma_f32_16x16x32_bf16 v[52:55], v[216:219], v[0:3], v[96:99]
	v_mfma_f32_16x16x32_bf16 v[0:3], v[208:211], v[12:15], v[140:143]
	v_mfma_f32_16x16x32_bf16 v[12:15], v[220:223], v[12:15], v[116:119]
	s_waitcnt lgkmcnt(4)
	v_mfma_f32_16x16x32_bf16 v[144:147], v[148:151], v[76:79], v[180:183]
	v_mfma_f32_16x16x32_bf16 v[116:119], v[152:155], v[76:79], v[184:187]
	v_mfma_f32_16x16x32_bf16 v[140:143], v[156:159], v[76:79], v[188:191]
	v_mfma_f32_16x16x32_bf16 v[112:115], v[160:163], v[76:79], v[192:195]
	s_waitcnt lgkmcnt(3)
	v_mfma_f32_16x16x32_bf16 v[108:111], v[148:151], v[92:95], v[80:83]
	v_mfma_f32_16x16x32_bf16 v[100:103], v[152:155], v[92:95], v[84:87]
	v_mfma_f32_16x16x32_bf16 v[104:107], v[156:159], v[92:95], v[88:91]
	v_mfma_f32_16x16x32_bf16 v[96:99], v[160:163], v[92:95], v[176:179]
	s_waitcnt lgkmcnt(2)
	v_mfma_f32_16x16x32_bf16 v[92:95], v[148:151], v[164:167], v[64:67]
	v_mfma_f32_16x16x32_bf16 v[84:87], v[152:155], v[164:167], v[72:75]
	v_mfma_f32_16x16x32_bf16 v[88:91], v[156:159], v[164:167], v[68:71]
	v_mfma_f32_16x16x32_bf16 v[80:83], v[160:163], v[164:167], v[60:63]
	ds_read_b128 v[164:167], v241 offset:12864
	s_waitcnt lgkmcnt(2)
	v_mfma_f32_16x16x32_bf16 v[76:79], v[148:151], v[168:171], v[44:47]
	v_mfma_f32_16x16x32_bf16 v[68:71], v[152:155], v[168:171], v[48:51]
	v_mfma_f32_16x16x32_bf16 v[72:75], v[156:159], v[168:171], v[52:55]
	v_mfma_f32_16x16x32_bf16 v[64:67], v[160:163], v[168:171], v[56:59]
	ds_read_b128 v[168:171], v241 offset:15424
	s_waitcnt lgkmcnt(2)
	v_mfma_f32_16x16x32_bf16 v[60:63], v[148:151], v[172:175], v[28:31]
	s_waitcnt lgkmcnt(0)
	v_mfma_f32_16x16x32_bf16 v[28:31], v[148:151], v[168:171], v[16:19]
	v_mfma_f32_16x16x32_bf16 v[16:19], v[160:163], v[168:171], v[120:123]
	s_nop 2
	v_mul_f32_e32 v123, 0xbfb8aa3b, v144
	v_mfma_f32_16x16x32_bf16 v[52:55], v[152:155], v[172:175], v[32:35]
	v_exp_f32_e32 v123, v123
	v_add_u32_e32 v122, s13, v240
	v_lshl_add_u64 v[120:121], v[202:203], 0, v[196:197]
	v_mfma_f32_16x16x32_bf16 v[56:59], v[156:159], v[172:175], v[36:39]
	v_add_f32_e32 v123, 1.0, v123
	v_mfma_f32_16x16x32_bf16 v[48:51], v[160:163], v[172:175], v[40:43]
	ds_read_b128 v[172:175], v247 offset:64
	v_mfma_f32_16x16x32_bf16 v[32:35], v[160:163], v[164:167], v[12:15]
	s_waitcnt lgkmcnt(0)
	v_mfma_f32_16x16x32_bf16 v[12:15], v[148:151], v[172:175], v[124:127]
	s_nop 2
	v_rcp_f32_e32 v126, v123
	v_mul_f32_e32 v123, 0xbfb8aa3b, v145
	v_exp_f32_e32 v123, v123
	v_mfma_f32_16x16x32_bf16 v[36:39], v[152:155], v[164:167], v[4:7]
	v_mad_i64_i32 v[124:125], s[2:3], v122, s46, v[120:121]
	v_add_f32_e32 v123, 1.0, v123
	v_rcp_f32_e32 v127, v123
	v_mul_f32_e32 v123, 0xbfb8aa3b, v146
	v_exp_f32_e32 v123, v123
	v_mfma_f32_16x16x32_bf16 v[4:7], v[152:155], v[172:175], v[128:131]
	v_mul_f32_e64 v126, v144, v126
	v_mul_f32_e64 v127, v145, v127
	v_add_f32_e32 v123, 1.0, v123
	v_rcp_f32_e32 v128, v123
	v_mul_f32_e32 v123, 0xbfb8aa3b, v147
	v_exp_f32_e32 v123, v123
	v_pk_mul_f32 v[126:127], v[140:141], v[126:127]
	v_mfma_f32_16x16x32_bf16 v[44:47], v[148:151], v[164:167], v[0:3]
	v_cvt_pk_bf16_f32 v126, v126, v127
	v_add_f32_e32 v123, 1.0, v123
	v_rcp_f32_e32 v129, v123
	v_mul_f32_e32 v123, 0xbfb8aa3b, v116
	v_exp_f32_e32 v123, v123
	v_mfma_f32_16x16x32_bf16 v[40:43], v[156:159], v[164:167], v[8:11]
	v_mul_f32_e64 v128, v146, v128
	v_mul_f32_e64 v129, v147, v129
	v_add_f32_e32 v123, 1.0, v123
	v_pk_mul_f32 v[128:129], v[142:143], v[128:129]
	v_mfma_f32_16x16x32_bf16 v[24:27], v[156:159], v[168:171], v[24:27]
	v_cvt_pk_bf16_f32 v127, v128, v129
	global_store_dwordx2 v[124:125], v[126:127], off
	v_rcp_f32_e32 v126, v123
	v_mul_f32_e32 v123, 0xbfb8aa3b, v117
	v_exp_f32_e32 v123, v123
	v_mfma_f32_16x16x32_bf16 v[20:23], v[152:155], v[168:171], v[20:23]
	v_add_f32_e32 v123, 1.0, v123
	v_rcp_f32_e32 v127, v123
	v_mfma_f32_16x16x32_bf16 v[8:11], v[156:159], v[172:175], v[132:135]
	v_mul_f32_e64 v116, v116, v126
	v_mul_f32_e64 v117, v117, v127
	v_pk_mul_f32 v[112:113], v[112:113], v[116:117]
	v_mfma_f32_16x16x32_bf16 v[0:3], v[160:163], v[172:175], v[136:139]
	v_cvt_pk_bf16_f32 v112, v112, v113
	v_mul_f32_e32 v113, 0xbfb8aa3b, v118
	v_exp_f32_e32 v113, v113
	s_nop 0
	v_add_f32_e32 v113, 1.0, v113
	v_rcp_f32_e32 v116, v113
	v_mul_f32_e32 v113, 0xbfb8aa3b, v119
	v_exp_f32_e32 v113, v113
	s_nop 0
	v_add_f32_e32 v113, 1.0, v113
	v_rcp_f32_e32 v117, v113
	s_nop 0
	v_pk_mul_f32 v[116:117], v[118:119], v[116:117]
	s_nop 0
	v_pk_mul_f32 v[114:115], v[114:115], v[116:117]
	s_nop 0
	v_cvt_pk_bf16_f32 v113, v114, v115
	v_mul_f32_e32 v114, 0xbfb8aa3b, v108
	v_mul_f32_e32 v115, 0xbfb8aa3b, v109
	v_exp_f32_e32 v114, v114
	v_exp_f32_e32 v115, v115
	global_store_dwordx2 v[124:125], v[112:113], off offset:32
	v_or_b32_e32 v112, 16, v122
	v_add_f32_e32 v114, 1.0, v114
	v_add_f32_e32 v115, 1.0, v115
	v_rcp_f32_e32 v114, v114
	v_rcp_f32_e32 v115, v115
	v_mad_i64_i32 v[112:113], s[2:3], v112, s46, v[120:121]
	v_pk_mul_f32 v[108:109], v[108:109], v[114:115]
	s_nop 0
	v_pk_mul_f32 v[104:105], v[104:105], v[108:109]
	s_nop 0
	v_cvt_pk_bf16_f32 v104, v104, v105
	v_mul_f32_e32 v105, 0xbfb8aa3b, v110
	v_exp_f32_e32 v105, v105
	s_nop 0
	v_add_f32_e32 v105, 1.0, v105
	v_rcp_f32_e32 v108, v105
	v_mul_f32_e32 v105, 0xbfb8aa3b, v111
	v_exp_f32_e32 v105, v105
	s_nop 0
	v_add_f32_e32 v105, 1.0, v105
	v_rcp_f32_e32 v109, v105
	s_nop 0
	v_pk_mul_f32 v[108:109], v[110:111], v[108:109]
	s_nop 0
	v_pk_mul_f32 v[106:107], v[106:107], v[108:109]
	s_nop 0
	v_cvt_pk_bf16_f32 v105, v106, v107
	global_store_dwordx2 v[112:113], v[104:105], off
	v_mul_f32_e32 v104, 0xbfb8aa3b, v100
	v_mul_f32_e32 v105, 0xbfb8aa3b, v101
	v_exp_f32_e32 v104, v104
	v_exp_f32_e32 v105, v105
	v_add_f32_e32 v104, 1.0, v104
	v_add_f32_e32 v105, 1.0, v105
	v_rcp_f32_e32 v104, v104
	v_rcp_f32_e32 v105, v105
	s_nop 0
	v_pk_mul_f32 v[100:101], v[100:101], v[104:105]
	s_nop 0
	v_pk_mul_f32 v[96:97], v[96:97], v[100:101]
	s_nop 0
	v_cvt_pk_bf16_f32 v96, v96, v97
	v_mul_f32_e32 v97, 0xbfb8aa3b, v102
	v_exp_f32_e32 v97, v97
	s_nop 0
	v_add_f32_e32 v97, 1.0, v97
	v_rcp_f32_e32 v100, v97
	v_mul_f32_e32 v97, 0xbfb8aa3b, v103
	v_exp_f32_e32 v97, v97
	s_nop 0
	v_add_f32_e32 v97, 1.0, v97
	v_rcp_f32_e32 v101, v97
	s_nop 0
	v_pk_mul_f32 v[100:101], v[102:103], v[100:101]
	s_nop 0
	v_pk_mul_f32 v[98:99], v[98:99], v[100:101]
	s_nop 0
	v_cvt_pk_bf16_f32 v97, v98, v99
	v_mul_f32_e32 v98, 0xbfb8aa3b, v92
	v_mul_f32_e32 v99, 0xbfb8aa3b, v93
	v_exp_f32_e32 v98, v98
	v_exp_f32_e32 v99, v99
	global_store_dwordx2 v[112:113], v[96:97], off offset:32
	v_or_b32_e32 v96, 32, v122
	v_add_f32_e32 v98, 1.0, v98
	v_add_f32_e32 v99, 1.0, v99
	v_rcp_f32_e32 v98, v98
	v_rcp_f32_e32 v99, v99
	v_mad_i64_i32 v[96:97], s[2:3], v96, s46, v[120:121]
	v_pk_mul_f32 v[92:93], v[92:93], v[98:99]
	s_nop 0
	v_pk_mul_f32 v[88:89], v[88:89], v[92:93]
	s_nop 0
	v_cvt_pk_bf16_f32 v88, v88, v89
	v_mul_f32_e32 v89, 0xbfb8aa3b, v94
	v_exp_f32_e32 v89, v89
	s_nop 0
	v_add_f32_e32 v89, 1.0, v89
	v_rcp_f32_e32 v92, v89
	v_mul_f32_e32 v89, 0xbfb8aa3b, v95
	v_exp_f32_e32 v89, v89
	s_nop 0
	v_add_f32_e32 v89, 1.0, v89
	v_rcp_f32_e32 v93, v89
	s_nop 0
	v_pk_mul_f32 v[92:93], v[94:95], v[92:93]
	s_nop 0
	v_pk_mul_f32 v[90:91], v[90:91], v[92:93]
	s_nop 0
	v_cvt_pk_bf16_f32 v89, v90, v91
	global_store_dwordx2 v[96:97], v[88:89], off
	v_mul_f32_e32 v88, 0xbfb8aa3b, v84
	v_mul_f32_e32 v89, 0xbfb8aa3b, v85
	v_exp_f32_e32 v88, v88
	v_exp_f32_e32 v89, v89
	v_add_f32_e32 v88, 1.0, v88
	v_add_f32_e32 v89, 1.0, v89
	v_rcp_f32_e32 v88, v88
	v_rcp_f32_e32 v89, v89
	s_nop 0
	v_pk_mul_f32 v[84:85], v[84:85], v[88:89]
	s_nop 0
	v_pk_mul_f32 v[80:81], v[80:81], v[84:85]
	s_nop 0
	v_cvt_pk_bf16_f32 v80, v80, v81
	v_mul_f32_e32 v81, 0xbfb8aa3b, v86
	v_exp_f32_e32 v81, v81
	s_nop 0
	v_add_f32_e32 v81, 1.0, v81
	v_rcp_f32_e32 v84, v81
	v_mul_f32_e32 v81, 0xbfb8aa3b, v87
	v_exp_f32_e32 v81, v81
	s_nop 0
	v_add_f32_e32 v81, 1.0, v81
	v_rcp_f32_e32 v85, v81
	s_nop 0
	v_pk_mul_f32 v[84:85], v[86:87], v[84:85]
	s_nop 0
	v_pk_mul_f32 v[82:83], v[82:83], v[84:85]
	s_nop 0
	v_cvt_pk_bf16_f32 v81, v82, v83
	v_mul_f32_e32 v82, 0xbfb8aa3b, v76
	v_mul_f32_e32 v83, 0xbfb8aa3b, v77
	v_exp_f32_e32 v82, v82
	v_exp_f32_e32 v83, v83
	global_store_dwordx2 v[96:97], v[80:81], off offset:32
	v_or_b32_e32 v80, 48, v122
	v_add_f32_e32 v82, 1.0, v82
	v_add_f32_e32 v83, 1.0, v83
	v_rcp_f32_e32 v82, v82
	v_rcp_f32_e32 v83, v83
	v_mad_i64_i32 v[80:81], s[2:3], v80, s46, v[120:121]
	v_pk_mul_f32 v[76:77], v[76:77], v[82:83]
	s_nop 0
	v_pk_mul_f32 v[72:73], v[72:73], v[76:77]
	s_nop 0
	v_cvt_pk_bf16_f32 v72, v72, v73
	v_mul_f32_e32 v73, 0xbfb8aa3b, v78
	v_exp_f32_e32 v73, v73
	s_nop 0
	v_add_f32_e32 v73, 1.0, v73
	v_rcp_f32_e32 v76, v73
	v_mul_f32_e32 v73, 0xbfb8aa3b, v79
	v_exp_f32_e32 v73, v73
	s_nop 0
	v_add_f32_e32 v73, 1.0, v73
	v_rcp_f32_e32 v77, v73
	s_nop 0
	v_pk_mul_f32 v[76:77], v[78:79], v[76:77]
	s_nop 0
	v_pk_mul_f32 v[74:75], v[74:75], v[76:77]
	s_nop 0
	v_cvt_pk_bf16_f32 v73, v74, v75
	global_store_dwordx2 v[80:81], v[72:73], off
	v_mul_f32_e32 v72, 0xbfb8aa3b, v68
	v_mul_f32_e32 v73, 0xbfb8aa3b, v69
	v_exp_f32_e32 v72, v72
	v_exp_f32_e32 v73, v73
	v_add_f32_e32 v72, 1.0, v72
	v_add_f32_e32 v73, 1.0, v73
	v_rcp_f32_e32 v72, v72
	v_rcp_f32_e32 v73, v73
	s_nop 0
	v_pk_mul_f32 v[68:69], v[68:69], v[72:73]
	s_nop 0
	v_pk_mul_f32 v[64:65], v[64:65], v[68:69]
	s_nop 0
	v_cvt_pk_bf16_f32 v64, v64, v65
	v_mul_f32_e32 v65, 0xbfb8aa3b, v70
	v_exp_f32_e32 v65, v65
	s_nop 0
	v_add_f32_e32 v65, 1.0, v65
	v_rcp_f32_e32 v68, v65
	v_mul_f32_e32 v65, 0xbfb8aa3b, v71
	v_exp_f32_e32 v65, v65
	s_nop 0
	v_add_f32_e32 v65, 1.0, v65
	v_rcp_f32_e32 v69, v65
	s_nop 0
	v_pk_mul_f32 v[68:69], v[70:71], v[68:69]
	s_nop 0
	v_pk_mul_f32 v[66:67], v[66:67], v[68:69]
	s_nop 0
	v_cvt_pk_bf16_f32 v65, v66, v67
	v_mul_f32_e32 v66, 0xbfb8aa3b, v60
	v_mul_f32_e32 v67, 0xbfb8aa3b, v61
	v_exp_f32_e32 v66, v66
	v_exp_f32_e32 v67, v67
	global_store_dwordx2 v[80:81], v[64:65], off offset:32
	v_or_b32_e32 v64, 64, v122
	v_add_f32_e32 v66, 1.0, v66
	v_add_f32_e32 v67, 1.0, v67
	v_rcp_f32_e32 v66, v66
	v_rcp_f32_e32 v67, v67
	v_mad_i64_i32 v[64:65], s[2:3], v64, s46, v[120:121]
	v_pk_mul_f32 v[60:61], v[60:61], v[66:67]
	s_nop 0
	v_pk_mul_f32 v[56:57], v[56:57], v[60:61]
	s_nop 0
	v_cvt_pk_bf16_f32 v56, v56, v57
	v_mul_f32_e32 v57, 0xbfb8aa3b, v62
	v_exp_f32_e32 v57, v57
	s_nop 0
	v_add_f32_e32 v57, 1.0, v57
	v_rcp_f32_e32 v60, v57
	v_mul_f32_e32 v57, 0xbfb8aa3b, v63
	v_exp_f32_e32 v57, v57
	s_nop 0
	v_add_f32_e32 v57, 1.0, v57
	v_rcp_f32_e32 v61, v57
	s_nop 0
	v_pk_mul_f32 v[60:61], v[62:63], v[60:61]
	s_nop 0
	v_pk_mul_f32 v[58:59], v[58:59], v[60:61]
	s_nop 0
	v_cvt_pk_bf16_f32 v57, v58, v59
	global_store_dwordx2 v[64:65], v[56:57], off
	v_mul_f32_e32 v56, 0xbfb8aa3b, v52
	v_mul_f32_e32 v57, 0xbfb8aa3b, v53
	v_exp_f32_e32 v56, v56
	v_exp_f32_e32 v57, v57
	v_add_f32_e32 v56, 1.0, v56
	v_add_f32_e32 v57, 1.0, v57
	v_rcp_f32_e32 v56, v56
	v_rcp_f32_e32 v57, v57
	s_nop 0
	v_pk_mul_f32 v[52:53], v[52:53], v[56:57]
	s_nop 0
	v_pk_mul_f32 v[48:49], v[48:49], v[52:53]
	s_nop 0
	v_cvt_pk_bf16_f32 v48, v48, v49
	v_mul_f32_e32 v49, 0xbfb8aa3b, v54
	v_exp_f32_e32 v49, v49
	s_nop 0
	v_add_f32_e32 v49, 1.0, v49
	v_rcp_f32_e32 v52, v49
	v_mul_f32_e32 v49, 0xbfb8aa3b, v55
	v_exp_f32_e32 v49, v49
	s_nop 0
	v_add_f32_e32 v49, 1.0, v49
	v_rcp_f32_e32 v53, v49
	s_nop 0
	v_pk_mul_f32 v[52:53], v[54:55], v[52:53]
	s_nop 0
	v_pk_mul_f32 v[50:51], v[50:51], v[52:53]
	s_nop 0
	v_cvt_pk_bf16_f32 v49, v50, v51
	v_mul_f32_e32 v50, 0xbfb8aa3b, v44
	v_mul_f32_e32 v51, 0xbfb8aa3b, v45
	v_exp_f32_e32 v50, v50
	v_exp_f32_e32 v51, v51
	global_store_dwordx2 v[64:65], v[48:49], off offset:32
	v_or_b32_e32 v48, 0x50, v122
	v_add_f32_e32 v50, 1.0, v50
	v_add_f32_e32 v51, 1.0, v51
	v_rcp_f32_e32 v50, v50
	v_rcp_f32_e32 v51, v51
	v_mad_i64_i32 v[48:49], s[2:3], v48, s46, v[120:121]
	v_pk_mul_f32 v[44:45], v[44:45], v[50:51]
	s_nop 0
	v_pk_mul_f32 v[40:41], v[40:41], v[44:45]
	s_nop 0
	v_cvt_pk_bf16_f32 v40, v40, v41
	v_mul_f32_e32 v41, 0xbfb8aa3b, v46
	v_exp_f32_e32 v41, v41
	s_nop 0
	v_add_f32_e32 v41, 1.0, v41
	v_rcp_f32_e32 v44, v41
	v_mul_f32_e32 v41, 0xbfb8aa3b, v47
	v_exp_f32_e32 v41, v41
	s_nop 0
	v_add_f32_e32 v41, 1.0, v41
	v_rcp_f32_e32 v45, v41
	s_nop 0
	v_pk_mul_f32 v[44:45], v[46:47], v[44:45]
	s_nop 0
	v_pk_mul_f32 v[42:43], v[42:43], v[44:45]
	s_nop 0
	v_cvt_pk_bf16_f32 v41, v42, v43
	global_store_dwordx2 v[48:49], v[40:41], off
	v_mul_f32_e32 v40, 0xbfb8aa3b, v36
	v_mul_f32_e32 v41, 0xbfb8aa3b, v37
	v_exp_f32_e32 v40, v40
	v_exp_f32_e32 v41, v41
	v_add_f32_e32 v40, 1.0, v40
	v_add_f32_e32 v41, 1.0, v41
	v_rcp_f32_e32 v40, v40
	v_rcp_f32_e32 v41, v41
	s_nop 0
	v_pk_mul_f32 v[36:37], v[36:37], v[40:41]
	s_nop 0
	v_pk_mul_f32 v[32:33], v[32:33], v[36:37]
	s_nop 0
	v_cvt_pk_bf16_f32 v32, v32, v33
	v_mul_f32_e32 v33, 0xbfb8aa3b, v38
	v_exp_f32_e32 v33, v33
	s_nop 0
	v_add_f32_e32 v33, 1.0, v33
	v_rcp_f32_e32 v36, v33
	v_mul_f32_e32 v33, 0xbfb8aa3b, v39
	v_exp_f32_e32 v33, v33
	s_nop 0
	v_add_f32_e32 v33, 1.0, v33
	v_rcp_f32_e32 v37, v33
	s_nop 0
	v_pk_mul_f32 v[36:37], v[38:39], v[36:37]
	s_nop 0
	v_pk_mul_f32 v[34:35], v[34:35], v[36:37]
	s_nop 0
	v_cvt_pk_bf16_f32 v33, v34, v35
	v_mul_f32_e32 v34, 0xbfb8aa3b, v28
	v_mul_f32_e32 v35, 0xbfb8aa3b, v29
	v_exp_f32_e32 v34, v34
	v_exp_f32_e32 v35, v35
	global_store_dwordx2 v[48:49], v[32:33], off offset:32
	v_or_b32_e32 v32, 0x60, v122
	v_add_f32_e32 v34, 1.0, v34
	v_add_f32_e32 v35, 1.0, v35
	v_rcp_f32_e32 v34, v34
	v_rcp_f32_e32 v35, v35
	v_mad_i64_i32 v[32:33], s[2:3], v32, s46, v[120:121]
	v_pk_mul_f32 v[28:29], v[28:29], v[34:35]
	s_nop 0
	v_pk_mul_f32 v[24:25], v[24:25], v[28:29]
	s_nop 0
	v_cvt_pk_bf16_f32 v24, v24, v25
	v_mul_f32_e32 v25, 0xbfb8aa3b, v30
	v_exp_f32_e32 v25, v25
	s_nop 0
	v_add_f32_e32 v25, 1.0, v25
	v_rcp_f32_e32 v28, v25
	v_mul_f32_e32 v25, 0xbfb8aa3b, v31
	v_exp_f32_e32 v25, v25
	s_nop 0
	v_add_f32_e32 v25, 1.0, v25
	v_rcp_f32_e32 v29, v25
	s_nop 0
	v_pk_mul_f32 v[28:29], v[30:31], v[28:29]
	s_nop 0
	v_pk_mul_f32 v[26:27], v[26:27], v[28:29]
	s_nop 0
	v_cvt_pk_bf16_f32 v25, v26, v27
	global_store_dwordx2 v[32:33], v[24:25], off
	v_mul_f32_e32 v24, 0xbfb8aa3b, v20
	v_mul_f32_e32 v25, 0xbfb8aa3b, v21
	v_exp_f32_e32 v24, v24
	v_exp_f32_e32 v25, v25
	v_add_f32_e32 v24, 1.0, v24
	v_add_f32_e32 v25, 1.0, v25
	v_rcp_f32_e32 v24, v24
	v_rcp_f32_e32 v25, v25
	s_nop 0
	v_pk_mul_f32 v[20:21], v[20:21], v[24:25]
	s_nop 0
	v_pk_mul_f32 v[16:17], v[16:17], v[20:21]
	s_nop 0
	v_cvt_pk_bf16_f32 v16, v16, v17
	v_mul_f32_e32 v17, 0xbfb8aa3b, v22
	v_exp_f32_e32 v17, v17
	s_nop 0
	v_add_f32_e32 v17, 1.0, v17
	v_rcp_f32_e32 v20, v17
	v_mul_f32_e32 v17, 0xbfb8aa3b, v23
	v_exp_f32_e32 v17, v17
	s_nop 0
	v_add_f32_e32 v17, 1.0, v17
	v_rcp_f32_e32 v21, v17
	s_nop 0
	v_pk_mul_f32 v[20:21], v[22:23], v[20:21]
	s_nop 0
	v_pk_mul_f32 v[18:19], v[18:19], v[20:21]
	s_nop 0
	v_cvt_pk_bf16_f32 v17, v18, v19
	v_mul_f32_e32 v18, 0xbfb8aa3b, v12
	v_mul_f32_e32 v19, 0xbfb8aa3b, v13
	v_exp_f32_e32 v18, v18
	v_exp_f32_e32 v19, v19
	global_store_dwordx2 v[32:33], v[16:17], off offset:32
	v_or_b32_e32 v16, 0x70, v122
	v_add_f32_e32 v18, 1.0, v18
	v_add_f32_e32 v19, 1.0, v19
	v_rcp_f32_e32 v18, v18
	v_rcp_f32_e32 v19, v19
	v_mad_i64_i32 v[16:17], s[2:3], v16, s46, v[120:121]
	v_readlane_b32 s2, v254, 22
	v_pk_mul_f32 v[12:13], v[12:13], v[18:19]
	s_add_i32 s10, s10, s2
	v_pk_mul_f32 v[8:9], v[8:9], v[12:13]
	s_cmpk_gt_u32 s12, 0x15f
	v_cvt_pk_bf16_f32 v8, v8, v9
	v_mul_f32_e32 v9, 0xbfb8aa3b, v14
	v_exp_f32_e32 v9, v9
	s_nop 0
	v_add_f32_e32 v9, 1.0, v9
	v_rcp_f32_e32 v12, v9
	v_mul_f32_e32 v9, 0xbfb8aa3b, v15
	v_exp_f32_e32 v9, v9
	s_nop 0
	v_add_f32_e32 v9, 1.0, v9
	v_rcp_f32_e32 v13, v9
	s_nop 0
	v_pk_mul_f32 v[12:13], v[14:15], v[12:13]
	s_nop 0
	v_pk_mul_f32 v[10:11], v[10:11], v[12:13]
	s_nop 0
	v_cvt_pk_bf16_f32 v9, v10, v11
	global_store_dwordx2 v[16:17], v[8:9], off
	v_mul_f32_e32 v8, 0xbfb8aa3b, v4
	v_mul_f32_e32 v9, 0xbfb8aa3b, v5
	v_exp_f32_e32 v8, v8
	v_exp_f32_e32 v9, v9
	v_add_f32_e32 v8, 1.0, v8
	v_add_f32_e32 v9, 1.0, v9
	v_rcp_f32_e32 v8, v8
	v_rcp_f32_e32 v9, v9
	s_nop 0
	v_pk_mul_f32 v[4:5], v[4:5], v[8:9]
	s_nop 0
	v_pk_mul_f32 v[0:1], v[0:1], v[4:5]
	s_nop 0
	v_cvt_pk_bf16_f32 v0, v0, v1
	v_mul_f32_e32 v1, 0xbfb8aa3b, v6
	v_exp_f32_e32 v1, v1
	s_nop 0
	v_add_f32_e32 v1, 1.0, v1
	v_rcp_f32_e32 v4, v1
	v_mul_f32_e32 v1, 0xbfb8aa3b, v7
	v_exp_f32_e32 v1, v1
	s_nop 0
	v_add_f32_e32 v1, 1.0, v1
	v_rcp_f32_e32 v5, v1
	s_nop 0
	v_pk_mul_f32 v[4:5], v[6:7], v[4:5]
	s_nop 0
	v_pk_mul_f32 v[2:3], v[2:3], v[4:5]
	s_nop 0
	v_cvt_pk_bf16_f32 v1, v2, v3
	global_store_dwordx2 v[16:17], v[0:1], off offset:32
	s_cbranch_scc0 .LBB0_850

.LBB0_910:
	s_lshl_b64 s[8:9], s[50:51], 1
	s_waitcnt vmcnt(63) expcnt(7) lgkmcnt(15)
	s_barrier
	s_waitcnt vmcnt(0)
	ds_write_b128 v240, v[44:47]
	ds_write_b128 v240, v[40:43] offset:5120
	ds_write_b128 v240, v[36:39] offset:10240
	ds_write_b128 v240, v[32:35] offset:15360
	ds_write_b128 v240, v[28:31] offset:20480
	ds_write_b128 v240, v[24:27] offset:25600
	ds_write_b128 v240, v[20:23] offset:30720
	ds_write_b128 v240, v[16:19] offset:35840
	ds_write_b128 v240, v[12:15] offset:40960
	ds_write_b128 v240, v[8:11] offset:46080
	ds_write_b128 v240, v[4:7] offset:51200
	ds_write_b128 v240, v[0:3] offset:56320
	v_lshl_add_u64 v[0:1], v[192:193], 0, s[8:9]
	v_lshl_add_u64 v[2:3], v[194:195], 0, s[8:9]
	v_lshl_add_u64 v[4:5], v[202:203], 1, v[0:1]
	v_lshl_add_u64 v[6:7], v[204:205], 1, v[0:1]
	v_lshl_add_u64 v[8:9], v[206:207], 1, v[0:1]
	v_lshl_add_u64 v[10:11], v[208:209], 1, v[0:1]
	v_lshl_add_u64 v[12:13], v[210:211], 1, v[0:1]
	v_lshl_add_u64 v[14:15], v[212:213], 1, v[0:1]
	v_lshl_add_u64 v[16:17], v[214:215], 1, v[0:1]
	v_lshl_add_u64 v[0:1], v[216:217], 1, v[0:1]
	v_lshl_add_u64 v[176:177], v[218:219], 1, v[2:3]
	v_lshl_add_u64 v[178:179], v[220:221], 1, v[2:3]
	v_lshl_add_u64 v[180:181], v[222:223], 1, v[2:3]
	v_lshl_add_u64 v[2:3], v[224:225], 1, v[2:3]
	s_waitcnt lgkmcnt(0)
	s_barrier
	global_load_dwordx4 v[44:47], v[4:5], off
	global_load_dwordx4 v[40:43], v[6:7], off
	global_load_dwordx4 v[36:39], v[8:9], off
	global_load_dwordx4 v[32:35], v[10:11], off
	global_load_dwordx4 v[28:31], v[12:13], off
	global_load_dwordx4 v[24:27], v[14:15], off
	global_load_dwordx4 v[20:23], v[16:17], off
	s_nop 0
	global_load_dwordx4 v[16:19], v[0:1], off
	global_load_dwordx4 v[12:15], v[176:177], off
	global_load_dwordx4 v[8:11], v[178:179], off
	global_load_dwordx4 v[4:7], v[180:181], off
	s_nop 0
	global_load_dwordx4 v[0:3], v[2:3], off
	ds_read_b128 v[176:179], v241 offset:40960
	ds_read_b128 v[184:187], v241 offset:43520
	ds_read_b128 v[188:191], v241 offset:46080
	ds_read_b128 v[230:233], v241 offset:48640
	ds_read_b128 v[180:183], v239
	ds_read_b128 v[244:247], v239 offset:2560
	s_add_i32 s2, s2, -1
	s_add_i32 s50, s50, 64
	s_waitcnt lgkmcnt(1)
	v_mfma_f32_16x16x32_bf16 v[60:63], v[176:179], v[180:183], v[60:63]
	v_mfma_f32_16x16x32_bf16 v[64:67], v[184:187], v[180:183], v[64:67]
	v_mfma_f32_16x16x32_bf16 v[68:71], v[188:191], v[180:183], v[68:71]
	v_mfma_f32_16x16x32_bf16 v[76:79], v[230:233], v[180:183], v[76:79]
	ds_read_b128 v[180:183], v239 offset:5120
	s_waitcnt lgkmcnt(1)
	v_mfma_f32_16x16x32_bf16 v[72:75], v[176:179], v[244:247], v[72:75]
	v_mfma_f32_16x16x32_bf16 v[56:59], v[184:187], v[244:247], v[56:59]
	v_mfma_f32_16x16x32_bf16 v[52:55], v[188:191], v[244:247], v[52:55]
	v_mfma_f32_16x16x32_bf16 v[48:51], v[230:233], v[244:247], v[48:51]
	ds_read_b128 v[244:247], v239 offset:7680
	s_waitcnt lgkmcnt(1)
	v_mfma_f32_16x16x32_bf16 v[104:107], v[176:179], v[180:183], v[104:107]
	v_mfma_f32_16x16x32_bf16 v[92:95], v[184:187], v[180:183], v[92:95]
	v_mfma_f32_16x16x32_bf16 v[84:87], v[188:191], v[180:183], v[84:87]
	v_mfma_f32_16x16x32_bf16 v[80:83], v[230:233], v[180:183], v[80:83]
	ds_read_b128 v[180:183], v239 offset:10240
	s_waitcnt lgkmcnt(1)
	v_mfma_f32_16x16x32_bf16 v[120:123], v[176:179], v[244:247], v[120:123]
	v_mfma_f32_16x16x32_bf16 v[108:111], v[184:187], v[244:247], v[108:111]
	v_mfma_f32_16x16x32_bf16 v[96:99], v[188:191], v[244:247], v[96:99]
	v_mfma_f32_16x16x32_bf16 v[88:91], v[230:233], v[244:247], v[88:91]
	ds_read_b128 v[244:247], v239 offset:12800
	s_waitcnt lgkmcnt(1)
	v_mfma_f32_16x16x32_bf16 v[132:135], v[176:179], v[180:183], v[132:135]
	v_mfma_f32_16x16x32_bf16 v[124:127], v[184:187], v[180:183], v[124:127]
	v_mfma_f32_16x16x32_bf16 v[112:115], v[188:191], v[180:183], v[112:115]
	v_mfma_f32_16x16x32_bf16 v[100:103], v[230:233], v[180:183], v[100:103]
	ds_read_b128 v[180:183], v239 offset:15360
	s_waitcnt lgkmcnt(1)
	v_mfma_f32_16x16x32_bf16 v[140:143], v[176:179], v[244:247], v[140:143]
	v_mfma_f32_16x16x32_bf16 v[136:139], v[184:187], v[244:247], v[136:139]
	v_mfma_f32_16x16x32_bf16 v[128:131], v[188:191], v[244:247], v[128:131]
	v_mfma_f32_16x16x32_bf16 v[116:119], v[230:233], v[244:247], v[116:119]
	ds_read_b128 v[244:247], v242
	s_waitcnt lgkmcnt(1)
	v_mfma_f32_16x16x32_bf16 v[156:159], v[176:179], v[180:183], v[156:159]
	v_mfma_f32_16x16x32_bf16 v[152:155], v[184:187], v[180:183], v[152:155]
	v_mfma_f32_16x16x32_bf16 v[148:151], v[188:191], v[180:183], v[148:151]
	v_mfma_f32_16x16x32_bf16 v[144:147], v[230:233], v[180:183], v[144:147]
	ds_read_b128 v[180:183], v239 offset:64
	s_waitcnt lgkmcnt(1)
	v_mfma_f32_16x16x32_bf16 v[160:163], v[176:179], v[244:247], v[160:163]
	ds_read_b128 v[176:179], v241 offset:41024
	v_mfma_f32_16x16x32_bf16 v[164:167], v[184:187], v[244:247], v[164:167]
	ds_read_b128 v[184:187], v241 offset:43584
	v_mfma_f32_16x16x32_bf16 v[168:171], v[188:191], v[244:247], v[168:171]
	ds_read_b128 v[188:191], v241 offset:46144
	v_mfma_f32_16x16x32_bf16 v[172:175], v[230:233], v[244:247], v[172:175]
	ds_read_b128 v[230:233], v241 offset:48704
	ds_read_b128 v[244:247], v239 offset:2624
	s_waitcnt lgkmcnt(1)
	v_mfma_f32_16x16x32_bf16 v[60:63], v[176:179], v[180:183], v[60:63]
	v_mfma_f32_16x16x32_bf16 v[64:67], v[184:187], v[180:183], v[64:67]
	v_mfma_f32_16x16x32_bf16 v[68:71], v[188:191], v[180:183], v[68:71]
	v_mfma_f32_16x16x32_bf16 v[76:79], v[230:233], v[180:183], v[76:79]
	ds_read_b128 v[180:183], v239 offset:5184
	s_waitcnt lgkmcnt(1)
	v_mfma_f32_16x16x32_bf16 v[72:75], v[176:179], v[244:247], v[72:75]
	v_mfma_f32_16x16x32_bf16 v[56:59], v[184:187], v[244:247], v[56:59]
	v_mfma_f32_16x16x32_bf16 v[52:55], v[188:191], v[244:247], v[52:55]
	v_mfma_f32_16x16x32_bf16 v[48:51], v[230:233], v[244:247], v[48:51]
	ds_read_b128 v[244:247], v239 offset:7744
	s_waitcnt lgkmcnt(1)
	v_mfma_f32_16x16x32_bf16 v[104:107], v[176:179], v[180:183], v[104:107]
	v_mfma_f32_16x16x32_bf16 v[92:95], v[184:187], v[180:183], v[92:95]
	v_mfma_f32_16x16x32_bf16 v[84:87], v[188:191], v[180:183], v[84:87]
	v_mfma_f32_16x16x32_bf16 v[80:83], v[230:233], v[180:183], v[80:83]
	ds_read_b128 v[180:183], v239 offset:10304
	s_waitcnt lgkmcnt(1)
	v_mfma_f32_16x16x32_bf16 v[120:123], v[176:179], v[244:247], v[120:123]
	v_mfma_f32_16x16x32_bf16 v[108:111], v[184:187], v[244:247], v[108:111]
	v_mfma_f32_16x16x32_bf16 v[96:99], v[188:191], v[244:247], v[96:99]
	v_mfma_f32_16x16x32_bf16 v[88:91], v[230:233], v[244:247], v[88:91]
	ds_read_b128 v[244:247], v239 offset:12864
	s_waitcnt lgkmcnt(1)
	v_mfma_f32_16x16x32_bf16 v[132:135], v[176:179], v[180:183], v[132:135]
	v_mfma_f32_16x16x32_bf16 v[124:127], v[184:187], v[180:183], v[124:127]
	v_mfma_f32_16x16x32_bf16 v[112:115], v[188:191], v[180:183], v[112:115]
	v_mfma_f32_16x16x32_bf16 v[100:103], v[230:233], v[180:183], v[100:103]
	ds_read_b128 v[180:183], v239 offset:15424
	s_waitcnt lgkmcnt(1)
	v_mfma_f32_16x16x32_bf16 v[140:143], v[176:179], v[244:247], v[140:143]
	v_mfma_f32_16x16x32_bf16 v[136:139], v[184:187], v[244:247], v[136:139]
	v_mfma_f32_16x16x32_bf16 v[128:131], v[188:191], v[244:247], v[128:131]
	v_mfma_f32_16x16x32_bf16 v[116:119], v[230:233], v[244:247], v[116:119]
	ds_read_b128 v[244:247], v242 offset:64
	s_waitcnt lgkmcnt(1)
	v_mfma_f32_16x16x32_bf16 v[156:159], v[176:179], v[180:183], v[156:159]
	v_mfma_f32_16x16x32_bf16 v[152:155], v[184:187], v[180:183], v[152:155]
	v_mfma_f32_16x16x32_bf16 v[148:151], v[188:191], v[180:183], v[148:151]
	v_mfma_f32_16x16x32_bf16 v[144:147], v[230:233], v[180:183], v[144:147]
	s_waitcnt lgkmcnt(0)
	v_mfma_f32_16x16x32_bf16 v[160:163], v[176:179], v[244:247], v[160:163]
	v_mfma_f32_16x16x32_bf16 v[164:167], v[184:187], v[244:247], v[164:167]
	v_mfma_f32_16x16x32_bf16 v[168:171], v[188:191], v[244:247], v[168:171]
	v_mfma_f32_16x16x32_bf16 v[172:175], v[230:233], v[244:247], v[172:175]
	s_cmp_eq_u32 s2, 0
	s_cbranch_scc0 .LBB0_910
	s_add_i32 s2, s15, 0xffffe000
	s_ashr_i32 s2, s2, 12
	s_mulk_i32 s2, 0x1800
	s_add_i32 s8, s2, 0x1800
	s_and_b64 s[2:3], s[18:19], exec
	s_cselect_b32 s8, 0, s8
	s_ashr_i32 s9, s8, 31
	s_barrier
	s_waitcnt vmcnt(11)
	ds_write_b128 v240, v[44:47]
	s_waitcnt vmcnt(10)
	ds_write_b128 v240, v[40:43] offset:5120
	s_waitcnt vmcnt(9)
	ds_write_b128 v240, v[36:39] offset:10240
	s_waitcnt vmcnt(8)
	ds_write_b128 v240, v[32:35] offset:15360
	s_waitcnt vmcnt(7)
	ds_write_b128 v240, v[28:31] offset:20480
	s_waitcnt vmcnt(6)
	ds_write_b128 v240, v[24:27] offset:25600
	s_waitcnt vmcnt(5)
	ds_write_b128 v240, v[20:23] offset:30720
	s_waitcnt vmcnt(4)
	ds_write_b128 v240, v[16:19] offset:35840
	s_waitcnt vmcnt(3)
	ds_write_b128 v240, v[12:15] offset:40960
	s_waitcnt vmcnt(2)
	ds_write_b128 v240, v[8:11] offset:46080
	s_waitcnt vmcnt(1)
	ds_write_b128 v240, v[4:7] offset:51200
	s_waitcnt vmcnt(0)
	ds_write_b128 v240, v[0:3] offset:56320
	s_waitcnt lgkmcnt(0)
	s_barrier
	ds_read_b128 v[0:3], v241 offset:40960
	ds_read_b128 v[4:7], v241 offset:43520
	ds_read_b128 v[8:11], v241 offset:46080
	ds_read_b128 v[12:15], v241 offset:48640
	ds_read_b128 v[16:19], v239 offset:2560
	ds_read_b128 v[20:23], v239 offset:5120
	ds_read_b128 v[24:27], v239
	ds_read_b128 v[40:43], v239 offset:7680
	s_lshl_b64 s[2:3], s[8:9], 2
	s_waitcnt lgkmcnt(3)
	v_mfma_f32_16x16x32_bf16 v[44:47], v[0:3], v[16:19], v[72:75]
	s_add_u32 s2, s11, s2
	s_addc_u32 s3, s12, s3
	v_mov_b32_e32 v201, v197
	s_waitcnt lgkmcnt(1)
	v_mfma_f32_16x16x32_bf16 v[28:31], v[0:3], v[24:27], v[60:63]
	ds_read_b128 v[72:75], v239 offset:12800
	s_add_i32 s14, s14, s53
	s_cmp_gt_u32 s14, 63
	v_mfma_f32_16x16x32_bf16 v[32:35], v[4:7], v[24:27], v[64:67]
	v_mfma_f32_16x16x32_bf16 v[36:39], v[8:11], v[24:27], v[68:71]
	v_mfma_f32_16x16x32_bf16 v[24:27], v[12:15], v[24:27], v[76:79]
	v_mfma_f32_16x16x32_bf16 v[56:59], v[4:7], v[16:19], v[56:59]
	v_mfma_f32_16x16x32_bf16 v[52:55], v[8:11], v[16:19], v[52:55]
	v_mfma_f32_16x16x32_bf16 v[16:19], v[12:15], v[16:19], v[48:51]
	s_nop 2
	ds_read_b128 v[48:51], v239 offset:10240
	v_mfma_f32_16x16x32_bf16 v[60:63], v[0:3], v[20:23], v[104:107]
	v_mfma_f32_16x16x32_bf16 v[64:67], v[4:7], v[20:23], v[92:95]
	v_mfma_f32_16x16x32_bf16 v[68:71], v[8:11], v[20:23], v[84:87]
	s_nop 1
	ds_read_b128 v[92:95], v242
	v_mfma_f32_16x16x32_bf16 v[20:23], v[12:15], v[20:23], v[80:83]
	s_waitcnt lgkmcnt(3)
	v_mfma_f32_16x16x32_bf16 v[76:79], v[0:3], v[40:43], v[120:123]
	v_mfma_f32_16x16x32_bf16 v[80:83], v[4:7], v[40:43], v[108:111]
	v_mfma_f32_16x16x32_bf16 v[84:87], v[8:11], v[40:43], v[96:99]
	v_mfma_f32_16x16x32_bf16 v[40:43], v[12:15], v[40:43], v[88:91]
	s_nop 2
	ds_read_b128 v[88:91], v239 offset:15360
	s_waitcnt lgkmcnt(2)
	v_mfma_f32_16x16x32_bf16 v[176:179], v[0:3], v[48:51], v[132:135]
	v_mfma_f32_16x16x32_bf16 v[180:183], v[4:7], v[48:51], v[124:127]
	v_mfma_f32_16x16x32_bf16 v[184:187], v[8:11], v[48:51], v[112:115]
	v_mfma_f32_16x16x32_bf16 v[48:51], v[12:15], v[48:51], v[100:103]
	v_mfma_f32_16x16x32_bf16 v[188:191], v[0:3], v[72:75], v[140:143]
	v_mfma_f32_16x16x32_bf16 v[202:205], v[4:7], v[72:75], v[136:139]
	v_mfma_f32_16x16x32_bf16 v[206:209], v[8:11], v[72:75], v[128:131]
	v_mfma_f32_16x16x32_bf16 v[210:213], v[12:15], v[72:75], v[116:119]
	s_waitcnt lgkmcnt(0)
	v_mfma_f32_16x16x32_bf16 v[156:159], v[0:3], v[88:91], v[156:159]
	v_mfma_f32_16x16x32_bf16 v[152:155], v[4:7], v[88:91], v[152:155]
	v_mfma_f32_16x16x32_bf16 v[148:151], v[8:11], v[88:91], v[148:151]
	v_mfma_f32_16x16x32_bf16 v[144:147], v[12:15], v[88:91], v[144:147]
	v_mfma_f32_16x16x32_bf16 v[0:3], v[0:3], v[92:95], v[160:163]
	v_mfma_f32_16x16x32_bf16 v[4:7], v[4:7], v[92:95], v[164:167]
	v_mfma_f32_16x16x32_bf16 v[8:11], v[8:11], v[92:95], v[168:171]
	v_mfma_f32_16x16x32_bf16 v[160:163], v[12:15], v[92:95], v[172:175]
	ds_read_b128 v[12:15], v241 offset:41024
	ds_read_b128 v[164:167], v241 offset:43584
	ds_read_b128 v[168:171], v241 offset:46144
	ds_read_b128 v[172:175], v241 offset:48704
	ds_read_b128 v[72:75], v239 offset:2624
	ds_read_b128 v[88:91], v239 offset:5184
	ds_read_b128 v[92:95], v239 offset:64
	s_waitcnt lgkmcnt(0)
	v_mfma_f32_16x16x32_bf16 v[128:131], v[172:175], v[92:95], v[24:27]
	s_nop 2
	ds_read_b128 v[24:27], v239 offset:7744
	v_mfma_f32_16x16x32_bf16 v[116:119], v[168:171], v[72:75], v[52:55]
	v_mfma_f32_16x16x32_bf16 v[112:115], v[172:175], v[72:75], v[16:19]
	s_nop 1
	ds_read_b128 v[52:55], v239 offset:15424
	ds_read_b128 v[16:19], v239 offset:10304
	v_mfma_f32_16x16x32_bf16 v[108:111], v[12:15], v[88:91], v[60:63]
	v_mfma_f32_16x16x32_bf16 v[96:99], v[172:175], v[88:91], v[20:23]
	s_nop 1
	ds_read_b128 v[60:63], v242 offset:64
	ds_read_b128 v[20:23], v239 offset:12864
	v_mfma_f32_16x16x32_bf16 v[140:143], v[12:15], v[92:95], v[28:31]
	v_mfma_f32_16x16x32_bf16 v[136:139], v[164:167], v[92:95], v[32:35]
	v_mfma_f32_16x16x32_bf16 v[132:135], v[168:171], v[92:95], v[36:39]
	v_mfma_f32_16x16x32_bf16 v[124:127], v[12:15], v[72:75], v[44:47]
	v_mfma_f32_16x16x32_bf16 v[120:123], v[164:167], v[72:75], v[56:59]
	v_mfma_f32_16x16x32_bf16 v[104:107], v[164:167], v[88:91], v[64:67]
	v_mfma_f32_16x16x32_bf16 v[100:103], v[168:171], v[88:91], v[68:71]
	s_waitcnt lgkmcnt(4)
	v_mfma_f32_16x16x32_bf16 v[92:95], v[12:15], v[24:27], v[76:79]
	v_mfma_f32_16x16x32_bf16 v[88:91], v[164:167], v[24:27], v[80:83]
	v_mfma_f32_16x16x32_bf16 v[80:83], v[172:175], v[24:27], v[40:43]
	s_waitcnt lgkmcnt(2)
	v_mfma_f32_16x16x32_bf16 v[76:79], v[12:15], v[16:19], v[176:179]
	v_mfma_f32_16x16x32_bf16 v[72:75], v[164:167], v[16:19], v[180:183]
	v_mfma_f32_16x16x32_bf16 v[64:67], v[168:171], v[16:19], v[184:187]
	v_mfma_f32_16x16x32_bf16 v[56:59], v[172:175], v[16:19], v[48:51]
	s_waitcnt lgkmcnt(0)
	v_mfma_f32_16x16x32_bf16 v[48:51], v[12:15], v[20:23], v[188:191]
	v_mfma_f32_16x16x32_bf16 v[44:47], v[164:167], v[20:23], v[202:205]
	v_mfma_f32_16x16x32_bf16 v[40:43], v[168:171], v[20:23], v[206:209]
	v_mfma_f32_16x16x32_bf16 v[36:39], v[172:175], v[20:23], v[210:213]
	v_mfma_f32_16x16x32_bf16 v[32:35], v[12:15], v[52:55], v[156:159]
	v_mfma_f32_16x16x32_bf16 v[20:23], v[172:175], v[52:55], v[144:147]
	v_mfma_f32_16x16x32_bf16 v[16:19], v[12:15], v[60:63], v[0:3]
	s_nop 1
	v_add_u32_e32 v146, s15, v238
	v_ashrrev_i32_e32 v147, 31, v146
	v_mfma_f32_16x16x32_bf16 v[12:15], v[164:167], v[60:63], v[4:7]
	s_nop 2
	v_or_b32_e32 v4, s16, v226
	v_lshlrev_b32_e32 v196, 2, v4
	v_mfma_f32_16x16x32_bf16 v[84:87], v[168:171], v[24:27], v[84:87]
	v_lshl_add_u64 v[4:5], s[2:3], 0, v[196:197]
	v_lshl_add_u64 v[144:145], v[198:199], 0, v[196:197]
	v_lshl_add_u64 v[4:5], v[4:5], 0, v[200:201]
	v_mfma_f32_16x16x32_bf16 v[24:27], v[168:171], v[52:55], v[148:151]
	s_nop 2
	v_lshlrev_b64 v[148:149], 12, v[146:147]
	v_mfma_f32_16x16x32_bf16 v[28:31], v[164:167], v[52:55], v[152:155]
	s_nop 2
	v_lshl_add_u64 v[152:153], v[144:145], 0, v[148:149]
	v_mfma_f32_16x16x32_bf16 v[8:11], v[168:171], v[60:63], v[8:11]
	v_mfma_f32_16x16x32_bf16 v[0:3], v[172:175], v[60:63], v[160:163]
	global_load_dwordx4 v[68:71], v[4:5], off
	global_load_dwordx4 v[60:63], v[4:5], off offset:64
	global_load_dwordx4 v[52:55], v[4:5], off offset:128
	s_nop 0
	global_load_dwordx4 v[4:7], v[4:5], off offset:192
	s_nop 0
	global_load_dwordx4 v[148:151], v[152:153], off
	s_waitcnt vmcnt(0)
	v_pk_fma_f32 v[142:143], v[142:143], v[70:71], v[150:151]
	v_pk_fma_f32 v[140:141], v[140:141], v[68:69], v[148:149]
	global_store_dwordx4 v[152:153], v[140:143], off
	global_load_dwordx4 v[140:143], v[152:153], off offset:64
	s_waitcnt vmcnt(0)
	v_pk_fma_f32 v[138:139], v[138:139], v[62:63], v[142:143]
	v_pk_fma_f32 v[136:137], v[136:137], v[60:61], v[140:141]
	global_store_dwordx4 v[152:153], v[136:139], off offset:64
	global_load_dwordx4 v[136:139], v[152:153], off offset:128
	s_waitcnt vmcnt(0)
	v_pk_fma_f32 v[134:135], v[134:135], v[54:55], v[138:139]
	v_pk_fma_f32 v[132:133], v[132:133], v[52:53], v[136:137]
	global_store_dwordx4 v[152:153], v[132:135], off offset:128
	global_load_dwordx4 v[132:135], v[152:153], off offset:192
	s_waitcnt vmcnt(0)
	v_pk_fma_f32 v[130:131], v[130:131], v[6:7], v[134:135]
	v_pk_fma_f32 v[128:129], v[128:129], v[4:5], v[132:133]
	global_store_dwordx4 v[152:153], v[128:131], off offset:192
	s_nop 1
	v_or_b32_e32 v128, 16, v146
	v_ashrrev_i32_e32 v129, 31, v128
	v_lshlrev_b64 v[128:129], 12, v[128:129]
	v_lshl_add_u64 v[132:133], v[144:145], 0, v[128:129]
	global_load_dwordx4 v[128:131], v[132:133], off
	s_waitcnt vmcnt(0)
	v_pk_fma_f32 v[126:127], v[126:127], v[70:71], v[130:131]
	v_pk_fma_f32 v[124:125], v[124:125], v[68:69], v[128:129]
	global_store_dwordx4 v[132:133], v[124:127], off
	global_load_dwordx4 v[124:127], v[132:133], off offset:64
	s_waitcnt vmcnt(0)
	v_pk_fma_f32 v[122:123], v[122:123], v[62:63], v[126:127]
	v_pk_fma_f32 v[120:121], v[120:121], v[60:61], v[124:125]
	global_store_dwordx4 v[132:133], v[120:123], off offset:64
	global_load_dwordx4 v[120:123], v[132:133], off offset:128
	s_waitcnt vmcnt(0)
	v_pk_fma_f32 v[118:119], v[118:119], v[54:55], v[122:123]
	v_pk_fma_f32 v[116:117], v[116:117], v[52:53], v[120:121]
	global_store_dwordx4 v[132:133], v[116:119], off offset:128
	global_load_dwordx4 v[116:119], v[132:133], off offset:192
	s_waitcnt vmcnt(0)
	v_pk_fma_f32 v[114:115], v[114:115], v[6:7], v[118:119]
	v_pk_fma_f32 v[112:113], v[112:113], v[4:5], v[116:117]
	global_store_dwordx4 v[132:133], v[112:115], off offset:192
	s_nop 1
	v_or_b32_e32 v112, 32, v146
	v_ashrrev_i32_e32 v113, 31, v112
	v_lshlrev_b64 v[112:113], 12, v[112:113]
	v_lshl_add_u64 v[116:117], v[144:145], 0, v[112:113]
	global_load_dwordx4 v[112:115], v[116:117], off
	s_waitcnt vmcnt(0)
	v_pk_fma_f32 v[110:111], v[110:111], v[70:71], v[114:115]
	v_pk_fma_f32 v[108:109], v[108:109], v[68:69], v[112:113]
	global_store_dwordx4 v[116:117], v[108:111], off
	global_load_dwordx4 v[108:111], v[116:117], off offset:64
	s_waitcnt vmcnt(0)
	v_pk_fma_f32 v[106:107], v[106:107], v[62:63], v[110:111]
	v_pk_fma_f32 v[104:105], v[104:105], v[60:61], v[108:109]
	global_store_dwordx4 v[116:117], v[104:107], off offset:64
	global_load_dwordx4 v[104:107], v[116:117], off offset:128
	s_waitcnt vmcnt(0)
	v_pk_fma_f32 v[102:103], v[102:103], v[54:55], v[106:107]
	v_pk_fma_f32 v[100:101], v[100:101], v[52:53], v[104:105]
	global_store_dwordx4 v[116:117], v[100:103], off offset:128
	global_load_dwordx4 v[100:103], v[116:117], off offset:192
	s_waitcnt vmcnt(0)
	v_pk_fma_f32 v[98:99], v[98:99], v[6:7], v[102:103]
	v_pk_fma_f32 v[96:97], v[96:97], v[4:5], v[100:101]
	global_store_dwordx4 v[116:117], v[96:99], off offset:192
	s_nop 1
	v_or_b32_e32 v96, 48, v146
	v_ashrrev_i32_e32 v97, 31, v96
	v_lshlrev_b64 v[96:97], 12, v[96:97]
	v_lshl_add_u64 v[100:101], v[144:145], 0, v[96:97]
	global_load_dwordx4 v[96:99], v[100:101], off
	s_waitcnt vmcnt(0)
	v_pk_fma_f32 v[94:95], v[94:95], v[70:71], v[98:99]
	v_pk_fma_f32 v[92:93], v[92:93], v[68:69], v[96:97]
	global_store_dwordx4 v[100:101], v[92:95], off
	global_load_dwordx4 v[92:95], v[100:101], off offset:64
	s_waitcnt vmcnt(0)
	v_pk_fma_f32 v[90:91], v[90:91], v[62:63], v[94:95]
	v_pk_fma_f32 v[88:89], v[88:89], v[60:61], v[92:93]
	global_store_dwordx4 v[100:101], v[88:91], off offset:64
	global_load_dwordx4 v[88:91], v[100:101], off offset:128
	s_waitcnt vmcnt(0)
	v_pk_fma_f32 v[86:87], v[86:87], v[54:55], v[90:91]
	v_pk_fma_f32 v[84:85], v[84:85], v[52:53], v[88:89]
	global_store_dwordx4 v[100:101], v[84:87], off offset:128
	global_load_dwordx4 v[84:87], v[100:101], off offset:192
	s_waitcnt vmcnt(0)
	v_pk_fma_f32 v[82:83], v[82:83], v[6:7], v[86:87]
	v_pk_fma_f32 v[80:81], v[80:81], v[4:5], v[84:85]
	global_store_dwordx4 v[100:101], v[80:83], off offset:192
	s_nop 1
	v_or_b32_e32 v80, 64, v146
	v_ashrrev_i32_e32 v81, 31, v80
	v_lshlrev_b64 v[80:81], 12, v[80:81]
	v_lshl_add_u64 v[84:85], v[144:145], 0, v[80:81]
	global_load_dwordx4 v[80:83], v[84:85], off
	s_waitcnt vmcnt(0)
	v_pk_fma_f32 v[78:79], v[78:79], v[70:71], v[82:83]
	v_pk_fma_f32 v[76:77], v[76:77], v[68:69], v[80:81]
	global_store_dwordx4 v[84:85], v[76:79], off
	global_load_dwordx4 v[76:79], v[84:85], off offset:64
	s_waitcnt vmcnt(0)
	v_pk_fma_f32 v[74:75], v[74:75], v[62:63], v[78:79]
	v_pk_fma_f32 v[72:73], v[72:73], v[60:61], v[76:77]
	global_store_dwordx4 v[84:85], v[72:75], off offset:64
	global_load_dwordx4 v[72:75], v[84:85], off offset:128
	s_waitcnt vmcnt(0)
	v_pk_fma_f32 v[66:67], v[66:67], v[54:55], v[74:75]
	v_pk_fma_f32 v[64:65], v[64:65], v[52:53], v[72:73]
	global_store_dwordx4 v[84:85], v[64:67], off offset:128
	global_load_dwordx4 v[64:67], v[84:85], off offset:192
	s_waitcnt vmcnt(0)
	v_pk_fma_f32 v[58:59], v[58:59], v[6:7], v[66:67]
	v_pk_fma_f32 v[56:57], v[56:57], v[4:5], v[64:65]
	global_store_dwordx4 v[84:85], v[56:59], off offset:192
	s_nop 1
	v_or_b32_e32 v56, 0x50, v146
	v_ashrrev_i32_e32 v57, 31, v56
	v_lshlrev_b64 v[56:57], 12, v[56:57]
	v_lshl_add_u64 v[64:65], v[144:145], 0, v[56:57]
	global_load_dwordx4 v[56:59], v[64:65], off
	s_waitcnt vmcnt(0)
	v_pk_fma_f32 v[50:51], v[50:51], v[70:71], v[58:59]
	v_pk_fma_f32 v[48:49], v[48:49], v[68:69], v[56:57]
	global_store_dwordx4 v[64:65], v[48:51], off
	global_load_dwordx4 v[48:51], v[64:65], off offset:64
	s_waitcnt vmcnt(0)
	v_pk_fma_f32 v[46:47], v[46:47], v[62:63], v[50:51]
	v_pk_fma_f32 v[44:45], v[44:45], v[60:61], v[48:49]
	global_store_dwordx4 v[64:65], v[44:47], off offset:64
	global_load_dwordx4 v[44:47], v[64:65], off offset:128
	s_waitcnt vmcnt(0)
	v_pk_fma_f32 v[42:43], v[42:43], v[54:55], v[46:47]
	v_pk_fma_f32 v[40:41], v[40:41], v[52:53], v[44:45]
	global_store_dwordx4 v[64:65], v[40:43], off offset:128
	global_load_dwordx4 v[40:43], v[64:65], off offset:192
	s_waitcnt vmcnt(0)
	v_pk_fma_f32 v[38:39], v[38:39], v[6:7], v[42:43]
	v_pk_fma_f32 v[36:37], v[36:37], v[4:5], v[40:41]
	global_store_dwordx4 v[64:65], v[36:39], off offset:192
	s_nop 1
	v_or_b32_e32 v36, 0x60, v146
	v_ashrrev_i32_e32 v37, 31, v36
	v_lshlrev_b64 v[36:37], 12, v[36:37]
	v_lshl_add_u64 v[40:41], v[144:145], 0, v[36:37]
	global_load_dwordx4 v[36:39], v[40:41], off
	s_waitcnt vmcnt(0)
	v_pk_fma_f32 v[34:35], v[34:35], v[70:71], v[38:39]
	v_pk_fma_f32 v[32:33], v[32:33], v[68:69], v[36:37]
	global_store_dwordx4 v[40:41], v[32:35], off
	global_load_dwordx4 v[32:35], v[40:41], off offset:64
	s_waitcnt vmcnt(0)
	v_pk_fma_f32 v[30:31], v[30:31], v[62:63], v[34:35]
	v_pk_fma_f32 v[28:29], v[28:29], v[60:61], v[32:33]
	global_store_dwordx4 v[40:41], v[28:31], off offset:64
	global_load_dwordx4 v[28:31], v[40:41], off offset:128
	s_waitcnt vmcnt(0)
	v_pk_fma_f32 v[26:27], v[26:27], v[54:55], v[30:31]
	v_pk_fma_f32 v[24:25], v[24:25], v[52:53], v[28:29]
	global_store_dwordx4 v[40:41], v[24:27], off offset:128
	global_load_dwordx4 v[24:27], v[40:41], off offset:192
	s_waitcnt vmcnt(0)
	v_pk_fma_f32 v[22:23], v[22:23], v[6:7], v[26:27]
	v_pk_fma_f32 v[20:21], v[20:21], v[4:5], v[24:25]
	global_store_dwordx4 v[40:41], v[20:23], off offset:192
	s_nop 1
	v_or_b32_e32 v20, 0x70, v146
	v_ashrrev_i32_e32 v21, 31, v20
	v_lshlrev_b64 v[20:21], 12, v[20:21]
	v_lshl_add_u64 v[20:21], v[144:145], 0, v[20:21]
	global_load_dwordx4 v[22:25], v[20:21], off
	s_waitcnt vmcnt(0)
	v_pk_fma_f32 v[18:19], v[18:19], v[70:71], v[24:25]
	v_pk_fma_f32 v[16:17], v[16:17], v[68:69], v[22:23]
	global_store_dwordx4 v[20:21], v[16:19], off
	global_load_dwordx4 v[16:19], v[20:21], off offset:64
	s_waitcnt vmcnt(0)
	v_pk_fma_f32 v[14:15], v[14:15], v[62:63], v[18:19]
	v_pk_fma_f32 v[12:13], v[12:13], v[60:61], v[16:17]
	global_store_dwordx4 v[20:21], v[12:15], off offset:64
	global_load_dwordx4 v[12:15], v[20:21], off offset:128
	s_waitcnt vmcnt(0)
	v_pk_fma_f32 v[10:11], v[10:11], v[54:55], v[14:15]
	v_pk_fma_f32 v[8:9], v[8:9], v[52:53], v[12:13]
	global_store_dwordx4 v[20:21], v[8:11], off offset:128
	global_load_dwordx4 v[8:11], v[20:21], off offset:192
	s_waitcnt vmcnt(0)
	v_pk_fma_f32 v[2:3], v[2:3], v[6:7], v[10:11]
	v_pk_fma_f32 v[0:1], v[0:1], v[4:5], v[8:9]
	global_store_dwordx4 v[20:21], v[0:3], off offset:192
	s_cbranch_scc0 .LBB0_909
